# widened SwiGLU/bf16 epilogue stores: v_permlane16_swap between nf pairs gives 8 consecutive bf16 per lane, dwordx4 instead of 2x dwordx2
# speedup vs baseline: 1.0225x; 1.0225x over previous
; #define LAS __attribute__((address_space(3)))
; DEVI int tidx() { int t = threadIdx.x; asm volatile("" : "+v"(t)); return t; }
;   const int tid = tidx(), lane = tid & 63, wid = tid >> 6;
;   const int wm = wid >> 1, wn = wid & 1, r16 = lane & 15, quad = lane >> 4;
;   f32x4 acc[4][8];
; #pragma unroll
;   for (int i = 0; i < 4; i++)
; #pragma unroll
;     for (int j = 0; j < 8; j++) acc[i][j] = (f32x4){0.f, 0.f, 0.f, 0.f};
;   const int nk = (nk_part < 0) ? (K >> 5) : nk_part;
;   const int lrow = tid >> 2, lpc = tid & 3;
;   const int lch = lpc ^ ((0x78 >> (((lrow >> 2) & 3) * 2)) & 3);
;   const u16* ga = A + (size_t)(m0 + lrow) * lda + kbeg + lch * 8;
;   const u16* gb = Bt + (size_t)(n0 + lrow) * K + kbeg + lch * 8;
;   const size_t ga1 = (size_t)64 * lda, gb1 = (size_t)64 * K;
;   const unsigned lds0 = (unsigned)(uintptr_t)(LAS char*)smem + (unsigned)__builtin_amdgcn_readfirstlane(wid) * 1024u;
;     ...
;   __syncthreads();
;   G2_STAGE(0); G2_STAGE(1);
;   const int fsw = (0x78 >> (((r16 >> 2) & 3) * 2)) & 3;
;   const int aoff = (wm * 128 + r16) * 64 + ((quad ^ fsw) << 4);
;   const int boff = 16384 + (wn * 64 + r16) * 64 + ((quad ^ fsw) << 4);
;     ...
;         const int hcol = (n0 >> 1) + wn * 32 + nf * 16 + quad * 4;
.Lt10_crd:
	s_cmp_lt_u32 s41, 64
	s_cselect_b32 s40, 1, 0
	v_readlane_b32 s2, v250, 5
	v_readlane_b32 s3, v250, 6
	v_readlane_b32 s43, v254, 62
	s_mul_i32 s36, s41, 0x80000
	s_add_u32 s10, s2, s36
	s_addc_u32 s11, s3, 0
	s_add_u32 s10, s10, 0x4200000
	s_addc_u32 s11, s11, 0
	s_mul_i32 s36, s43, 0xb00000
	s_mul_i32 s37, s38, 0x40000
	s_add_i32 s36, s36, s37
	s_add_u32 s12, s2, s36
	s_addc_u32 s13, s3, 0
	s_add_u32 s12, s12, 0x16e00000
	s_addc_u32 s13, s13, 0
	s_movk_i32 s9, 0x78
	v_lshrrev_b32_e32 v0, 2, v145
	v_and_b32_e32 v131, 3, v145
	v_bfe_u32 v136, v145, 4, 2
	v_lshlrev_b32_e32 v136, 1, v136
	v_lshrrev_b32_e64 v136, v136, s9
	v_and_b32_e32 v136, 3, v136
	v_xor_b32_e32 v131, v131, v136
	v_lshlrev_b32_e32 v131, 4, v131
	s_movk_i32 s37, 0x800
	v_mad_u32_u24 v0, v0, s37, v131
	v_bfe_u32 v137, v145, 2, 1
	s_movk_i32 s37, 0x7c0
	v_mul_u32_u24_e32 v136, s37, v137
	v_sub_u32_e32 v136, v0, v136
	v_mov_b32_e32 v137, 0
	v_lshl_add_u64 v[134:135], s[12:13], 0, v[136:137]
	v_bfe_u32 v137, v145, 2, 1
	s_mul_i32 s37, s40, 0x7c0
	v_mul_u32_u24_e32 v136, s37, v137
	v_sub_u32_e32 v0, v0, v136
	s_lshl_b32 s14, s40, 6
	s_add_i32 s14, s14, 64
	s_mov_b32 s15, 0
	v_lshl_add_u64 v[132:133], s[10:11], 0, v[0:1]
	v_bfe_u32 v136, v145, 2, 2
	v_lshlrev_b32_e32 v136, 1, v136
	v_lshrrev_b32_e64 v136, v136, s9
	v_and_b32_e32 v136, 3, v136
	v_bfe_u32 v137, v145, 4, 2
	v_xor_b32_e32 v136, v136, v137
	v_lshlrev_b32_e32 v136, 4, v136
	v_and_b32_e32 v131, 15, v145
	v_lshl_or_b32 v136, v131, 6, v136
	v_bfe_u32 v137, v145, 6, 1
	v_lshl_or_b32 v137, v137, 12, v136
	v_lshrrev_b32_e32 v0, 7, v145
	v_lshl_or_b32 v136, v0, 13, v136
	v_and_b32_e32 v140, 1, v131
	v_lshl_or_b32 v131, v0, 7, v131
	v_bfe_u32 v0, v145, 4, 1
	v_lshlrev_b32_e32 v0, 5, v0
	v_bfe_u32 v141, v145, 5, 1
	v_lshl_or_b32 v0, v141, 4, v0
	v_bfe_u32 v141, v145, 6, 1
	s_mul_i32 s36, s41, 0x160000
	s_lshl_b32 s37, s38, 7
	s_lshl_b32 s37, s37, s40
	s_add_i32 s36, s36, s37
	s_add_u32 s12, s2, s36
	s_addc_u32 s13, s3, 0
	s_add_u32 s12, s12, 0xef40000
	s_addc_u32 s13, s13, 0
	s_movk_i32 s37, 5632
	v_mad_u32_u24 v138, v131, s37, v0
	v_lshlrev_b32_e32 v139, 6, v141
	v_lshlrev_b32_e64 v139, s40, v139
	v_add_u32_e32 v138, v138, v139
	s_mul_i32 s37, s40, 5568
	v_mul_u32_u24_e32 v139, s37, v140
	v_sub_u32_e32 v138, v138, v139
	v_mov_b32_e32 v139, 0
	v_lshl_add_u64 v[140:141], s[12:13], 0, v[138:139]
	s_mov_b32 s2, 0x20000
	s_mov_b32 s3, 0
	v_lshrrev_b32_e32 v0, 6, v145
	v_lshlrev_b32_e32 v0, 10, v0
	s_nop 0
	v_readfirstlane_b32 s43, v0
	s_mov_b32 s39, m0
	s_mov_b32 s10, 128
	s_mov_b32 s11, 0
	v_mov_b32_e32 v2, 0
	v_mov_b32_e32 v3, 0
	v_mov_b32_e32 v4, 0
	v_mov_b32_e32 v5, 0
	v_mov_b32_e32 v6, 0
	v_mov_b32_e32 v7, 0
	v_mov_b32_e32 v8, 0
	v_mov_b32_e32 v9, 0
	v_mov_b32_e32 v10, 0
	v_mov_b32_e32 v11, 0
	v_mov_b32_e32 v12, 0
	v_mov_b32_e32 v13, 0
	v_mov_b32_e32 v14, 0
	v_mov_b32_e32 v15, 0
	v_mov_b32_e32 v16, 0
	v_mov_b32_e32 v17, 0
	v_mov_b32_e32 v18, 0
	v_mov_b32_e32 v19, 0
	v_mov_b32_e32 v20, 0
	v_mov_b32_e32 v21, 0
	v_mov_b32_e32 v22, 0
	v_mov_b32_e32 v23, 0
	v_mov_b32_e32 v24, 0
	v_mov_b32_e32 v25, 0
	v_mov_b32_e32 v26, 0
	v_mov_b32_e32 v27, 0
	v_mov_b32_e32 v28, 0
	v_mov_b32_e32 v29, 0
	v_mov_b32_e32 v30, 0
	v_mov_b32_e32 v31, 0
	v_mov_b32_e32 v32, 0
	v_mov_b32_e32 v33, 0
	v_mov_b32_e32 v34, 0
	v_mov_b32_e32 v35, 0
	v_mov_b32_e32 v36, 0
	v_mov_b32_e32 v37, 0
	v_mov_b32_e32 v38, 0
	v_mov_b32_e32 v39, 0
	v_mov_b32_e32 v40, 0
	v_mov_b32_e32 v41, 0
	v_mov_b32_e32 v42, 0
	v_mov_b32_e32 v43, 0
	v_mov_b32_e32 v44, 0
	v_mov_b32_e32 v45, 0
	v_mov_b32_e32 v46, 0
	v_mov_b32_e32 v47, 0
	v_mov_b32_e32 v48, 0
	v_mov_b32_e32 v49, 0
	v_mov_b32_e32 v50, 0
	v_mov_b32_e32 v51, 0
	v_mov_b32_e32 v52, 0
	v_mov_b32_e32 v53, 0
	v_mov_b32_e32 v54, 0
	v_mov_b32_e32 v55, 0
	v_mov_b32_e32 v56, 0
	v_mov_b32_e32 v57, 0
	v_mov_b32_e32 v58, 0
	v_mov_b32_e32 v59, 0
	v_mov_b32_e32 v60, 0
	v_mov_b32_e32 v61, 0
	v_mov_b32_e32 v62, 0
	v_mov_b32_e32 v63, 0
	v_mov_b32_e32 v64, 0
	v_mov_b32_e32 v65, 0
	v_mov_b32_e32 v66, 0
	v_mov_b32_e32 v67, 0
	v_mov_b32_e32 v68, 0
	v_mov_b32_e32 v69, 0
	v_mov_b32_e32 v70, 0
	v_mov_b32_e32 v71, 0
	v_mov_b32_e32 v72, 0
	v_mov_b32_e32 v73, 0
	v_mov_b32_e32 v74, 0
	v_mov_b32_e32 v75, 0
	v_mov_b32_e32 v76, 0
	v_mov_b32_e32 v77, 0
	v_mov_b32_e32 v78, 0
	v_mov_b32_e32 v79, 0
	v_mov_b32_e32 v80, 0
	v_mov_b32_e32 v81, 0
	v_mov_b32_e32 v82, 0
	v_mov_b32_e32 v83, 0
	v_mov_b32_e32 v84, 0
	v_mov_b32_e32 v85, 0
	v_mov_b32_e32 v86, 0
	v_mov_b32_e32 v87, 0
	v_mov_b32_e32 v88, 0
	v_mov_b32_e32 v89, 0
	v_mov_b32_e32 v90, 0
	v_mov_b32_e32 v91, 0
	v_mov_b32_e32 v92, 0
	v_mov_b32_e32 v93, 0
	v_mov_b32_e32 v94, 0
	v_mov_b32_e32 v95, 0
	v_mov_b32_e32 v96, 0
	v_mov_b32_e32 v97, 0
	v_mov_b32_e32 v98, 0
	v_mov_b32_e32 v99, 0
	v_mov_b32_e32 v100, 0
	v_mov_b32_e32 v101, 0
	v_mov_b32_e32 v102, 0
	v_mov_b32_e32 v103, 0
	v_mov_b32_e32 v104, 0
	v_mov_b32_e32 v105, 0
	v_mov_b32_e32 v106, 0
	v_mov_b32_e32 v107, 0
	v_mov_b32_e32 v108, 0
	v_mov_b32_e32 v109, 0
	v_mov_b32_e32 v110, 0
	v_mov_b32_e32 v111, 0
	v_mov_b32_e32 v112, 0
	v_mov_b32_e32 v113, 0
	v_mov_b32_e32 v114, 0
	v_mov_b32_e32 v115, 0
	v_mov_b32_e32 v116, 0
	v_mov_b32_e32 v117, 0
	v_mov_b32_e32 v118, 0
	v_mov_b32_e32 v119, 0
	v_mov_b32_e32 v120, 0
	v_mov_b32_e32 v121, 0
	v_mov_b32_e32 v122, 0
	v_mov_b32_e32 v123, 0
	v_mov_b32_e32 v124, 0
	v_mov_b32_e32 v125, 0
	v_mov_b32_e32 v126, 0
	v_mov_b32_e32 v127, 0
	v_mov_b32_e32 v128, 0
	v_mov_b32_e32 v129, 0
	s_barrier
;     ...
;   __syncthreads();
;   G2_STAGE(0); G2_STAGE(1);
;   const int fsw = (0x78 >> (((r16 >> 2) & 3) * 2)) & 3;
;   const int aoff = (wm * 128 + r16) * 64 + ((quad ^ fsw) << 4);
;   const int boff = 16384 + (wn * 64 + r16) * 64 + ((quad ^ fsw) << 4);
;   for (int kt = 0; kt < nk; kt++) {
;     if (kt + 1 < nk) asm volatile("s_waitcnt vmcnt(6)" ::: "memory");
;     else asm volatile("s_waitcnt vmcnt(0)" ::: "memory");
;     __builtin_amdgcn_s_barrier();
;     asm volatile("" ::: "memory");
;     if (kt + 2 < nk) G2_STAGE(kt + 2);
;     const char* cS = smem + (kt % 3) * 24576;
;     bf16x8 xa[8], wb[4];
; #pragma unroll
;     for (int f = 0; f < 8; f++) xa[f] = *(const bf16x8*)(cS + aoff + f * 1024);
; #pragma unroll
;     for (int f = 0; f < 4; f++) wb[f] = *(const bf16x8*)(cS + boff + f * 1024);
; #pragma unroll
;     for (int nf = 0; nf < 4; nf++)
; #pragma unroll
;       for (int mf = 0; mf < 8; mf++)
;         acc[nf][mf] = __builtin_amdgcn_mfma_f32_16x16x32_bf16(wb[nf], xa[mf], acc[nf][mf], 0, 0, 0);
;   }
	s_add_i32 s38, s43, 0x0
	s_mov_b32 m0, s38
	v_lshl_add_u64 v[142:143], v[132:133], 0, s[2:3]
	global_load_lds_dwordx4 v[132:133], off
	s_addk_i32 m0, 0x1000
	s_nop 0
	global_load_lds_dwordx4 v[142:143], off
	v_lshl_add_u64 v[142:143], v[142:143], 0, s[2:3]
	s_addk_i32 m0, 0x1000
	s_nop 0
	global_load_lds_dwordx4 v[142:143], off
	v_lshl_add_u64 v[142:143], v[142:143], 0, s[2:3]
	s_addk_i32 m0, 0x1000
	s_nop 0
	global_load_lds_dwordx4 v[142:143], off
	s_addk_i32 m0, 0x1000
	v_lshl_add_u64 v[142:143], v[134:135], 0, s[2:3]
	s_nop 0
	global_load_lds_dwordx4 v[134:135], off
	s_addk_i32 m0, 0x1000
	v_lshl_add_u64 v[132:133], v[132:133], 0, s[14:15]
	s_nop 0
	global_load_lds_dwordx4 v[142:143], off
	v_lshl_add_u64 v[134:135], v[134:135], 0, s[10:11]
	s_nop 0
	s_add_i32 s38, s43, 0x6000
	s_mov_b32 m0, s38
	v_lshl_add_u64 v[142:143], v[132:133], 0, s[2:3]
	global_load_lds_dwordx4 v[132:133], off
	s_addk_i32 m0, 0x1000
	s_nop 0
	global_load_lds_dwordx4 v[142:143], off
	v_lshl_add_u64 v[142:143], v[142:143], 0, s[2:3]
	s_addk_i32 m0, 0x1000
	s_nop 0
	global_load_lds_dwordx4 v[142:143], off
	v_lshl_add_u64 v[142:143], v[142:143], 0, s[2:3]
	s_addk_i32 m0, 0x1000
	s_nop 0
	global_load_lds_dwordx4 v[142:143], off
	s_addk_i32 m0, 0x1000
	v_lshl_add_u64 v[142:143], v[134:135], 0, s[2:3]
	s_nop 0
	global_load_lds_dwordx4 v[134:135], off
	s_addk_i32 m0, 0x1000
	v_lshl_add_u64 v[132:133], v[132:133], 0, s[14:15]
	s_nop 0
	global_load_lds_dwordx4 v[142:143], off
	v_lshl_add_u64 v[134:135], v[134:135], 0, s[10:11]
	s_nop 0
	s_add_i32 s38, s43, 0xc000
	s_mov_b32 m0, s38
	v_lshl_add_u64 v[142:143], v[132:133], 0, s[2:3]
	global_load_lds_dwordx4 v[132:133], off
	s_addk_i32 m0, 0x1000
	s_nop 0
	global_load_lds_dwordx4 v[142:143], off
	v_lshl_add_u64 v[142:143], v[142:143], 0, s[2:3]
	s_addk_i32 m0, 0x1000
	s_nop 0
	global_load_lds_dwordx4 v[142:143], off
	v_lshl_add_u64 v[142:143], v[142:143], 0, s[2:3]
	s_addk_i32 m0, 0x1000
	s_nop 0
	global_load_lds_dwordx4 v[142:143], off
	s_addk_i32 m0, 0x1000
	v_lshl_add_u64 v[142:143], v[134:135], 0, s[2:3]
	s_nop 0
	global_load_lds_dwordx4 v[134:135], off
	s_addk_i32 m0, 0x1000
	v_lshl_add_u64 v[132:133], v[132:133], 0, s[14:15]
	s_nop 0
	global_load_lds_dwordx4 v[142:143], off
	v_lshl_add_u64 v[134:135], v[134:135], 0, s[10:11]
	s_nop 0
	s_waitcnt vmcnt(12)
	s_barrier
	ds_read_b128 v[146:149], v136 offset:0
	ds_read_b128 v[152:155], v136 offset:1024
	ds_read_b128 v[156:159], v136 offset:2048
	ds_read_b128 v[162:165], v136 offset:3072
	ds_read_b128 v[166:169], v136 offset:4096
	ds_read_b128 v[170:173], v136 offset:5120
	ds_read_b128 v[176:179], v136 offset:6144
	ds_read_b128 v[180:183], v136 offset:7168
	ds_read_b128 v[184:187], v137 offset:16384
	ds_read_b128 v[188:191], v137 offset:17408
	ds_read_b128 v[192:195], v137 offset:18432
	ds_read_b128 v[196:199], v137 offset:19456
	s_movk_i32 s36, 0x6000
	s_mov_b32 s37, 0
	s_movk_i32 s9, 14
.Lt10_loop:
	s_waitcnt vmcnt(6) lgkmcnt(0)
	s_barrier
	v_add_u32_e32 v144, s36, v136
	v_mfma_f32_16x16x32_bf16 v[126:129], v[184:187], v[146:149], v[126:129]
	ds_read_b128 v[200:203], v144 offset:0
	v_mfma_f32_16x16x32_bf16 v[122:125], v[184:187], v[152:155], v[122:125]
	ds_read_b128 v[204:207], v144 offset:1024
	v_mfma_f32_16x16x32_bf16 v[118:121], v[184:187], v[156:159], v[118:121]
	ds_read_b128 v[208:211], v144 offset:2048
	v_mfma_f32_16x16x32_bf16 v[114:117], v[184:187], v[162:165], v[114:117]
	ds_read_b128 v[212:215], v144 offset:3072
	v_mfma_f32_16x16x32_bf16 v[110:113], v[184:187], v[166:169], v[110:113]
	ds_read_b128 v[216:219], v144 offset:4096
	v_mfma_f32_16x16x32_bf16 v[106:109], v[184:187], v[170:173], v[106:109]
	ds_read_b128 v[220:223], v144 offset:5120
	v_mfma_f32_16x16x32_bf16 v[102:105], v[184:187], v[176:179], v[102:105]
	ds_read_b128 v[224:227], v144 offset:6144
	v_mfma_f32_16x16x32_bf16 v[98:101], v[184:187], v[180:183], v[98:101]
	ds_read_b128 v[228:231], v144 offset:7168
	v_mfma_f32_16x16x32_bf16 v[94:97], v[188:191], v[146:149], v[94:97]
	v_add_u32_e32 v144, s36, v137
	v_mfma_f32_16x16x32_bf16 v[90:93], v[188:191], v[152:155], v[90:93]
	v_mfma_f32_16x16x32_bf16 v[86:89], v[188:191], v[156:159], v[86:89]
	ds_read_b128 v[232:235], v144 offset:16384
	v_mfma_f32_16x16x32_bf16 v[82:85], v[188:191], v[162:165], v[82:85]
	ds_read_b128 v[236:239], v144 offset:17408
	v_mfma_f32_16x16x32_bf16 v[78:81], v[188:191], v[166:169], v[78:81]
	ds_read_b128 v[240:243], v144 offset:18432
	v_mfma_f32_16x16x32_bf16 v[74:77], v[188:191], v[170:173], v[74:77]
	ds_read_b128 v[244:247], v144 offset:19456
	s_add_i32 s38, s43, s37
	v_mfma_f32_16x16x32_bf16 v[70:73], v[188:191], v[176:179], v[70:73]
	s_mov_b32 m0, s38
	v_lshl_add_u64 v[142:143], v[132:133], 0, s[2:3]
	v_mfma_f32_16x16x32_bf16 v[66:69], v[188:191], v[180:183], v[66:69]
	global_load_lds_dwordx4 v[132:133], off
	s_addk_i32 m0, 0x1000
	v_mfma_f32_16x16x32_bf16 v[62:65], v[192:195], v[146:149], v[62:65]
	v_mfma_f32_16x16x32_bf16 v[58:61], v[192:195], v[152:155], v[58:61]
	v_mfma_f32_16x16x32_bf16 v[54:57], v[192:195], v[156:159], v[54:57]
	global_load_lds_dwordx4 v[142:143], off
	v_lshl_add_u64 v[142:143], v[142:143], 0, s[2:3]
	s_addk_i32 m0, 0x1000
	v_mfma_f32_16x16x32_bf16 v[50:53], v[192:195], v[162:165], v[50:53]
	v_mfma_f32_16x16x32_bf16 v[46:49], v[192:195], v[166:169], v[46:49]
	v_mfma_f32_16x16x32_bf16 v[42:45], v[192:195], v[170:173], v[42:45]
	global_load_lds_dwordx4 v[142:143], off
	v_lshl_add_u64 v[142:143], v[142:143], 0, s[2:3]
	s_addk_i32 m0, 0x1000
	v_mfma_f32_16x16x32_bf16 v[38:41], v[192:195], v[176:179], v[38:41]
	v_mfma_f32_16x16x32_bf16 v[34:37], v[192:195], v[180:183], v[34:37]
	v_mfma_f32_16x16x32_bf16 v[30:33], v[196:199], v[146:149], v[30:33]
	global_load_lds_dwordx4 v[142:143], off
	s_addk_i32 m0, 0x1000
	v_lshl_add_u64 v[142:143], v[134:135], 0, s[2:3]
	v_mfma_f32_16x16x32_bf16 v[26:29], v[196:199], v[152:155], v[26:29]
	v_mfma_f32_16x16x32_bf16 v[22:25], v[196:199], v[156:159], v[22:25]
	v_mfma_f32_16x16x32_bf16 v[18:21], v[196:199], v[162:165], v[18:21]
	global_load_lds_dwordx4 v[134:135], off
	s_addk_i32 m0, 0x1000
	v_lshl_add_u64 v[132:133], v[132:133], 0, s[14:15]
	v_mfma_f32_16x16x32_bf16 v[14:17], v[196:199], v[166:169], v[14:17]
	v_mfma_f32_16x16x32_bf16 v[10:13], v[196:199], v[170:173], v[10:13]
	v_mfma_f32_16x16x32_bf16 v[6:9], v[196:199], v[176:179], v[6:9]
	global_load_lds_dwordx4 v[142:143], off
	v_lshl_add_u64 v[134:135], v[134:135], 0, s[10:11]
	v_mfma_f32_16x16x32_bf16 v[2:5], v[196:199], v[180:183], v[2:5]
	s_mov_b32 s37, s36
	s_add_i32 s36, s36, 0x6000
	s_cmp_eq_u32 s36, 0x12000
	s_cselect_b32 s36, 0, s36
	s_waitcnt vmcnt(6) lgkmcnt(0)
	s_barrier
;     ...
;   for (int kt = 0; kt < nk; kt++) {
;     if (kt + 1 < nk) asm volatile("s_waitcnt vmcnt(6)" ::: "memory");
;     else asm volatile("s_waitcnt vmcnt(0)" ::: "memory");
;     __builtin_amdgcn_s_barrier();
;     asm volatile("" ::: "memory");
;     if (kt + 2 < nk) G2_STAGE(kt + 2);
;     const char* cS = smem + (kt % 3) * 24576;
;     bf16x8 xa[8], wb[4];
; #pragma unroll
;     for (int f = 0; f < 8; f++) xa[f] = *(const bf16x8*)(cS + aoff + f * 1024);
; #pragma unroll
;     for (int f = 0; f < 4; f++) wb[f] = *(const bf16x8*)(cS + boff + f * 1024);
; #pragma unroll
;     for (int nf = 0; nf < 4; nf++)
; #pragma unroll
;       for (int mf = 0; mf < 8; mf++)
;         acc[nf][mf] = __builtin_amdgcn_mfma_f32_16x16x32_bf16(wb[nf], xa[mf], acc[nf][mf], 0, 0, 0);
;   }
	v_add_u32_e32 v144, s36, v136
	v_mfma_f32_16x16x32_bf16 v[126:129], v[232:235], v[200:203], v[126:129]
	ds_read_b128 v[146:149], v144 offset:0
	v_mfma_f32_16x16x32_bf16 v[122:125], v[232:235], v[204:207], v[122:125]
	ds_read_b128 v[152:155], v144 offset:1024
	v_mfma_f32_16x16x32_bf16 v[118:121], v[232:235], v[208:211], v[118:121]
	ds_read_b128 v[156:159], v144 offset:2048
	v_mfma_f32_16x16x32_bf16 v[114:117], v[232:235], v[212:215], v[114:117]
	ds_read_b128 v[162:165], v144 offset:3072
	v_mfma_f32_16x16x32_bf16 v[110:113], v[232:235], v[216:219], v[110:113]
	ds_read_b128 v[166:169], v144 offset:4096
	v_mfma_f32_16x16x32_bf16 v[106:109], v[232:235], v[220:223], v[106:109]
	ds_read_b128 v[170:173], v144 offset:5120
	v_mfma_f32_16x16x32_bf16 v[102:105], v[232:235], v[224:227], v[102:105]
	ds_read_b128 v[176:179], v144 offset:6144
	v_mfma_f32_16x16x32_bf16 v[98:101], v[232:235], v[228:231], v[98:101]
	ds_read_b128 v[180:183], v144 offset:7168
	v_mfma_f32_16x16x32_bf16 v[94:97], v[236:239], v[200:203], v[94:97]
	v_add_u32_e32 v144, s36, v137
	v_mfma_f32_16x16x32_bf16 v[90:93], v[236:239], v[204:207], v[90:93]
	v_mfma_f32_16x16x32_bf16 v[86:89], v[236:239], v[208:211], v[86:89]
	ds_read_b128 v[184:187], v144 offset:16384
	v_mfma_f32_16x16x32_bf16 v[82:85], v[236:239], v[212:215], v[82:85]
	ds_read_b128 v[188:191], v144 offset:17408
	v_mfma_f32_16x16x32_bf16 v[78:81], v[236:239], v[216:219], v[78:81]
	ds_read_b128 v[192:195], v144 offset:18432
	v_mfma_f32_16x16x32_bf16 v[74:77], v[236:239], v[220:223], v[74:77]
	ds_read_b128 v[196:199], v144 offset:19456
	s_add_i32 s38, s43, s37
	v_mfma_f32_16x16x32_bf16 v[70:73], v[236:239], v[224:227], v[70:73]
	s_mov_b32 m0, s38
	v_lshl_add_u64 v[142:143], v[132:133], 0, s[2:3]
	v_mfma_f32_16x16x32_bf16 v[66:69], v[236:239], v[228:231], v[66:69]
	global_load_lds_dwordx4 v[132:133], off
	s_addk_i32 m0, 0x1000
	v_mfma_f32_16x16x32_bf16 v[62:65], v[240:243], v[200:203], v[62:65]
	v_mfma_f32_16x16x32_bf16 v[58:61], v[240:243], v[204:207], v[58:61]
	v_mfma_f32_16x16x32_bf16 v[54:57], v[240:243], v[208:211], v[54:57]
	global_load_lds_dwordx4 v[142:143], off
	v_lshl_add_u64 v[142:143], v[142:143], 0, s[2:3]
	s_addk_i32 m0, 0x1000
	v_mfma_f32_16x16x32_bf16 v[50:53], v[240:243], v[212:215], v[50:53]
	v_mfma_f32_16x16x32_bf16 v[46:49], v[240:243], v[216:219], v[46:49]
	v_mfma_f32_16x16x32_bf16 v[42:45], v[240:243], v[220:223], v[42:45]
	global_load_lds_dwordx4 v[142:143], off
	v_lshl_add_u64 v[142:143], v[142:143], 0, s[2:3]
	s_addk_i32 m0, 0x1000
	v_mfma_f32_16x16x32_bf16 v[38:41], v[240:243], v[224:227], v[38:41]
	v_mfma_f32_16x16x32_bf16 v[34:37], v[240:243], v[228:231], v[34:37]
	v_mfma_f32_16x16x32_bf16 v[30:33], v[244:247], v[200:203], v[30:33]
	global_load_lds_dwordx4 v[142:143], off
	s_addk_i32 m0, 0x1000
	v_lshl_add_u64 v[142:143], v[134:135], 0, s[2:3]
	v_mfma_f32_16x16x32_bf16 v[26:29], v[244:247], v[204:207], v[26:29]
	v_mfma_f32_16x16x32_bf16 v[22:25], v[244:247], v[208:211], v[22:25]
	v_mfma_f32_16x16x32_bf16 v[18:21], v[244:247], v[212:215], v[18:21]
	global_load_lds_dwordx4 v[134:135], off
	s_addk_i32 m0, 0x1000
	v_lshl_add_u64 v[132:133], v[132:133], 0, s[14:15]
	v_mfma_f32_16x16x32_bf16 v[14:17], v[244:247], v[216:219], v[14:17]
	v_mfma_f32_16x16x32_bf16 v[10:13], v[244:247], v[220:223], v[10:13]
	v_mfma_f32_16x16x32_bf16 v[6:9], v[244:247], v[224:227], v[6:9]
	global_load_lds_dwordx4 v[142:143], off
	v_lshl_add_u64 v[134:135], v[134:135], 0, s[10:11]
	v_mfma_f32_16x16x32_bf16 v[2:5], v[244:247], v[228:231], v[2:5]
	s_mov_b32 s37, s36
	s_add_i32 s36, s36, 0x6000
	s_cmp_eq_u32 s36, 0x12000
	s_cselect_b32 s36, 0, s36
	s_sub_i32 s9, s9, 1
	s_cmp_lg_u32 s9, 0
	s_cbranch_scc1 .Lt10_loop
	s_waitcnt vmcnt(6) lgkmcnt(0)
	s_barrier
	v_add_u32_e32 v144, s36, v136
	v_mfma_f32_16x16x32_bf16 v[126:129], v[184:187], v[146:149], v[126:129]
	ds_read_b128 v[200:203], v144 offset:0
	v_mfma_f32_16x16x32_bf16 v[122:125], v[184:187], v[152:155], v[122:125]
	ds_read_b128 v[204:207], v144 offset:1024
	v_mfma_f32_16x16x32_bf16 v[118:121], v[184:187], v[156:159], v[118:121]
	ds_read_b128 v[208:211], v144 offset:2048
	v_mfma_f32_16x16x32_bf16 v[114:117], v[184:187], v[162:165], v[114:117]
	ds_read_b128 v[212:215], v144 offset:3072
	v_mfma_f32_16x16x32_bf16 v[110:113], v[184:187], v[166:169], v[110:113]
	ds_read_b128 v[216:219], v144 offset:4096
	v_mfma_f32_16x16x32_bf16 v[106:109], v[184:187], v[170:173], v[106:109]
	ds_read_b128 v[220:223], v144 offset:5120
	v_mfma_f32_16x16x32_bf16 v[102:105], v[184:187], v[176:179], v[102:105]
	ds_read_b128 v[224:227], v144 offset:6144
	v_mfma_f32_16x16x32_bf16 v[98:101], v[184:187], v[180:183], v[98:101]
	ds_read_b128 v[228:231], v144 offset:7168
	v_mfma_f32_16x16x32_bf16 v[94:97], v[188:191], v[146:149], v[94:97]
	v_add_u32_e32 v144, s36, v137
	v_mfma_f32_16x16x32_bf16 v[90:93], v[188:191], v[152:155], v[90:93]
	v_mfma_f32_16x16x32_bf16 v[86:89], v[188:191], v[156:159], v[86:89]
	ds_read_b128 v[232:235], v144 offset:16384
	v_mfma_f32_16x16x32_bf16 v[82:85], v[188:191], v[162:165], v[82:85]
	ds_read_b128 v[236:239], v144 offset:17408
	v_mfma_f32_16x16x32_bf16 v[78:81], v[188:191], v[166:169], v[78:81]
	ds_read_b128 v[240:243], v144 offset:18432
	v_mfma_f32_16x16x32_bf16 v[74:77], v[188:191], v[170:173], v[74:77]
	ds_read_b128 v[244:247], v144 offset:19456
	s_add_i32 s38, s43, s37
	v_mfma_f32_16x16x32_bf16 v[70:73], v[188:191], v[176:179], v[70:73]
	s_mov_b32 m0, s38
	v_lshl_add_u64 v[142:143], v[132:133], 0, s[2:3]
	v_mfma_f32_16x16x32_bf16 v[66:69], v[188:191], v[180:183], v[66:69]
	global_load_lds_dwordx4 v[132:133], off
	s_addk_i32 m0, 0x1000
	v_mfma_f32_16x16x32_bf16 v[62:65], v[192:195], v[146:149], v[62:65]
;     ...
;   for (int kt = 0; kt < nk; kt++) {
;     if (kt + 1 < nk) asm volatile("s_waitcnt vmcnt(6)" ::: "memory");
;     else asm volatile("s_waitcnt vmcnt(0)" ::: "memory");
;     __builtin_amdgcn_s_barrier();
;     asm volatile("" ::: "memory");
;     if (kt + 2 < nk) G2_STAGE(kt + 2);
;     const char* cS = smem + (kt % 3) * 24576;
;     bf16x8 xa[8], wb[4];
; #pragma unroll
;     for (int f = 0; f < 8; f++) xa[f] = *(const bf16x8*)(cS + aoff + f * 1024);
; #pragma unroll
;     for (int f = 0; f < 4; f++) wb[f] = *(const bf16x8*)(cS + boff + f * 1024);
; #pragma unroll
;     for (int nf = 0; nf < 4; nf++)
; #pragma unroll
;       for (int mf = 0; mf < 8; mf++)
;         acc[nf][mf] = __builtin_amdgcn_mfma_f32_16x16x32_bf16(wb[nf], xa[mf], acc[nf][mf], 0, 0, 0);
;   }
	v_mfma_f32_16x16x32_bf16 v[58:61], v[192:195], v[152:155], v[58:61]
	v_mfma_f32_16x16x32_bf16 v[54:57], v[192:195], v[156:159], v[54:57]
	global_load_lds_dwordx4 v[142:143], off
	v_lshl_add_u64 v[142:143], v[142:143], 0, s[2:3]
	s_addk_i32 m0, 0x1000
	v_mfma_f32_16x16x32_bf16 v[50:53], v[192:195], v[162:165], v[50:53]
	v_mfma_f32_16x16x32_bf16 v[46:49], v[192:195], v[166:169], v[46:49]
	v_mfma_f32_16x16x32_bf16 v[42:45], v[192:195], v[170:173], v[42:45]
	global_load_lds_dwordx4 v[142:143], off
	v_lshl_add_u64 v[142:143], v[142:143], 0, s[2:3]
	s_addk_i32 m0, 0x1000
	v_mfma_f32_16x16x32_bf16 v[38:41], v[192:195], v[176:179], v[38:41]
	v_mfma_f32_16x16x32_bf16 v[34:37], v[192:195], v[180:183], v[34:37]
	v_mfma_f32_16x16x32_bf16 v[30:33], v[196:199], v[146:149], v[30:33]
	global_load_lds_dwordx4 v[142:143], off
	s_addk_i32 m0, 0x1000
	v_lshl_add_u64 v[142:143], v[134:135], 0, s[2:3]
	v_mfma_f32_16x16x32_bf16 v[26:29], v[196:199], v[152:155], v[26:29]
	v_mfma_f32_16x16x32_bf16 v[22:25], v[196:199], v[156:159], v[22:25]
	v_mfma_f32_16x16x32_bf16 v[18:21], v[196:199], v[162:165], v[18:21]
	global_load_lds_dwordx4 v[134:135], off
	s_addk_i32 m0, 0x1000
	v_lshl_add_u64 v[132:133], v[132:133], 0, s[14:15]
	v_mfma_f32_16x16x32_bf16 v[14:17], v[196:199], v[166:169], v[14:17]
	v_mfma_f32_16x16x32_bf16 v[10:13], v[196:199], v[170:173], v[10:13]
	v_mfma_f32_16x16x32_bf16 v[6:9], v[196:199], v[176:179], v[6:9]
	global_load_lds_dwordx4 v[142:143], off
	v_lshl_add_u64 v[134:135], v[134:135], 0, s[10:11]
	v_mfma_f32_16x16x32_bf16 v[2:5], v[196:199], v[180:183], v[2:5]
	s_mov_b32 s37, s36
	s_add_i32 s36, s36, 0x6000
	s_cmp_eq_u32 s36, 0x12000
	s_cselect_b32 s36, 0, s36
	s_waitcnt vmcnt(6) lgkmcnt(0)
	s_barrier
	v_add_u32_e32 v144, s36, v136
	v_mfma_f32_16x16x32_bf16 v[126:129], v[232:235], v[200:203], v[126:129]
	ds_read_b128 v[146:149], v144 offset:0
	v_mfma_f32_16x16x32_bf16 v[122:125], v[232:235], v[204:207], v[122:125]
	ds_read_b128 v[152:155], v144 offset:1024
	v_mfma_f32_16x16x32_bf16 v[118:121], v[232:235], v[208:211], v[118:121]
	ds_read_b128 v[156:159], v144 offset:2048
	v_mfma_f32_16x16x32_bf16 v[114:117], v[232:235], v[212:215], v[114:117]
	ds_read_b128 v[162:165], v144 offset:3072
	v_mfma_f32_16x16x32_bf16 v[110:113], v[232:235], v[216:219], v[110:113]
	ds_read_b128 v[166:169], v144 offset:4096
	v_mfma_f32_16x16x32_bf16 v[106:109], v[232:235], v[220:223], v[106:109]
	ds_read_b128 v[170:173], v144 offset:5120
	v_mfma_f32_16x16x32_bf16 v[102:105], v[232:235], v[224:227], v[102:105]
	ds_read_b128 v[176:179], v144 offset:6144
	v_mfma_f32_16x16x32_bf16 v[98:101], v[232:235], v[228:231], v[98:101]
	ds_read_b128 v[180:183], v144 offset:7168
	v_mfma_f32_16x16x32_bf16 v[94:97], v[236:239], v[200:203], v[94:97]
	v_add_u32_e32 v144, s36, v137
	v_mfma_f32_16x16x32_bf16 v[90:93], v[236:239], v[204:207], v[90:93]
	v_mfma_f32_16x16x32_bf16 v[86:89], v[236:239], v[208:211], v[86:89]
	ds_read_b128 v[184:187], v144 offset:16384
	v_mfma_f32_16x16x32_bf16 v[82:85], v[236:239], v[212:215], v[82:85]
	ds_read_b128 v[188:191], v144 offset:17408
	v_mfma_f32_16x16x32_bf16 v[78:81], v[236:239], v[216:219], v[78:81]
	ds_read_b128 v[192:195], v144 offset:18432
	v_mfma_f32_16x16x32_bf16 v[74:77], v[236:239], v[220:223], v[74:77]
	ds_read_b128 v[196:199], v144 offset:19456
	v_mfma_f32_16x16x32_bf16 v[70:73], v[236:239], v[224:227], v[70:73]
	v_mfma_f32_16x16x32_bf16 v[66:69], v[236:239], v[228:231], v[66:69]
	v_mfma_f32_16x16x32_bf16 v[62:65], v[240:243], v[200:203], v[62:65]
	v_mfma_f32_16x16x32_bf16 v[58:61], v[240:243], v[204:207], v[58:61]
	v_mfma_f32_16x16x32_bf16 v[54:57], v[240:243], v[208:211], v[54:57]
	v_mfma_f32_16x16x32_bf16 v[50:53], v[240:243], v[212:215], v[50:53]
	v_mfma_f32_16x16x32_bf16 v[46:49], v[240:243], v[216:219], v[46:49]
	v_mfma_f32_16x16x32_bf16 v[42:45], v[240:243], v[220:223], v[42:45]
	v_mfma_f32_16x16x32_bf16 v[38:41], v[240:243], v[224:227], v[38:41]
	v_mfma_f32_16x16x32_bf16 v[34:37], v[240:243], v[228:231], v[34:37]
	v_mfma_f32_16x16x32_bf16 v[30:33], v[244:247], v[200:203], v[30:33]
	v_mfma_f32_16x16x32_bf16 v[26:29], v[244:247], v[204:207], v[26:29]
	v_mfma_f32_16x16x32_bf16 v[22:25], v[244:247], v[208:211], v[22:25]
	v_mfma_f32_16x16x32_bf16 v[18:21], v[244:247], v[212:215], v[18:21]
	v_mfma_f32_16x16x32_bf16 v[14:17], v[244:247], v[216:219], v[14:17]
	v_mfma_f32_16x16x32_bf16 v[10:13], v[244:247], v[220:223], v[10:13]
	v_mfma_f32_16x16x32_bf16 v[6:9], v[244:247], v[224:227], v[6:9]
	v_mfma_f32_16x16x32_bf16 v[2:5], v[244:247], v[228:231], v[2:5]
	s_mov_b32 s37, s36
	s_add_i32 s36, s36, 0x6000
	s_cmp_eq_u32 s36, 0x12000
	s_cselect_b32 s36, 0, s36
	s_waitcnt vmcnt(0) lgkmcnt(0)
	s_barrier
; DEVI unsigned pack2(float a, float b) { return __builtin_bit_cast(unsigned, __builtin_convertvector((f32x2_t){a, b}, bf16x2_t)); }
; DEVI float sigmoidf_(float x) { return __builtin_amdgcn_rcpf(1.f + __expf(-x)); }
; DEVI float siluf_(float x) { return x * __builtin_amdgcn_rcpf(1.f + __expf(-x)); }
;     ...
;   for (int kt = 0; kt < nk; kt++) {
;     if (kt + 1 < nk) asm volatile("s_waitcnt vmcnt(6)" ::: "memory");
;     else asm volatile("s_waitcnt vmcnt(0)" ::: "memory");
;     __builtin_amdgcn_s_barrier();
;     asm volatile("" ::: "memory");
;     if (kt + 2 < nk) G2_STAGE(kt + 2);
;     const char* cS = smem + (kt % 3) * 24576;
;     bf16x8 xa[8], wb[4];
; #pragma unroll
;     for (int f = 0; f < 8; f++) xa[f] = *(const bf16x8*)(cS + aoff + f * 1024);
; #pragma unroll
;     for (int f = 0; f < 4; f++) wb[f] = *(const bf16x8*)(cS + boff + f * 1024);
; #pragma unroll
;     for (int nf = 0; nf < 4; nf++)
; #pragma unroll
;       for (int mf = 0; mf < 8; mf++)
;         acc[nf][mf] = __builtin_amdgcn_mfma_f32_16x16x32_bf16(wb[nf], xa[mf], acc[nf][mf], 0, 0, 0);
;   }
;     ...
; #pragma unroll
;   for (int mf = 0; mf < 8; mf++) {
;     const int row = m0 + wm * 128 + mf * 16 + r16;
;     if (EPI == EPI_SWIGLU) {
; #pragma unroll
;       for (int nf = 0; nf < 2; nf++) {
;         const int hcol = (n0 >> 1) + wn * 32 + nf * 16 + quad * 4;
;         f32x4 g = acc[nf][mf], u = acc[nf + 2][mf];
;         u32x2 pk;
;         pk[0] = pack2(siluf_(g[0]) * u[0], siluf_(g[1]) * u[1]);
;         pk[1] = pack2(siluf_(g[2]) * u[2], siluf_(g[3]) * u[3]);
;         *(u32x2*)(outb + (size_t)row * DFF + hcol) = pk;
	v_add_u32_e32 v144, s36, v136
	v_mfma_f32_16x16x32_bf16 v[126:129], v[184:187], v[146:149], v[126:129]
	ds_read_b128 v[200:203], v144 offset:0
	v_mfma_f32_16x16x32_bf16 v[122:125], v[184:187], v[152:155], v[122:125]
	ds_read_b128 v[204:207], v144 offset:1024
	v_mfma_f32_16x16x32_bf16 v[118:121], v[184:187], v[156:159], v[118:121]
	ds_read_b128 v[208:211], v144 offset:2048
	v_mfma_f32_16x16x32_bf16 v[114:117], v[184:187], v[162:165], v[114:117]
	ds_read_b128 v[212:215], v144 offset:3072
	v_mfma_f32_16x16x32_bf16 v[110:113], v[184:187], v[166:169], v[110:113]
	ds_read_b128 v[216:219], v144 offset:4096
	v_mfma_f32_16x16x32_bf16 v[106:109], v[184:187], v[170:173], v[106:109]
	ds_read_b128 v[220:223], v144 offset:5120
	v_mfma_f32_16x16x32_bf16 v[102:105], v[184:187], v[176:179], v[102:105]
	ds_read_b128 v[224:227], v144 offset:6144
	v_mfma_f32_16x16x32_bf16 v[98:101], v[184:187], v[180:183], v[98:101]
	ds_read_b128 v[228:231], v144 offset:7168
	v_mfma_f32_16x16x32_bf16 v[94:97], v[188:191], v[146:149], v[94:97]
	v_add_u32_e32 v144, s36, v137
	v_mfma_f32_16x16x32_bf16 v[90:93], v[188:191], v[152:155], v[90:93]
	v_mfma_f32_16x16x32_bf16 v[86:89], v[188:191], v[156:159], v[86:89]
	ds_read_b128 v[232:235], v144 offset:16384
	v_mfma_f32_16x16x32_bf16 v[82:85], v[188:191], v[162:165], v[82:85]
	ds_read_b128 v[236:239], v144 offset:17408
	v_mfma_f32_16x16x32_bf16 v[78:81], v[188:191], v[166:169], v[78:81]
	ds_read_b128 v[240:243], v144 offset:18432
	v_mfma_f32_16x16x32_bf16 v[74:77], v[188:191], v[170:173], v[74:77]
	ds_read_b128 v[244:247], v144 offset:19456
	v_mfma_f32_16x16x32_bf16 v[70:73], v[188:191], v[176:179], v[70:73]
	v_mfma_f32_16x16x32_bf16 v[66:69], v[188:191], v[180:183], v[66:69]
	v_mfma_f32_16x16x32_bf16 v[62:65], v[192:195], v[146:149], v[62:65]
	v_mfma_f32_16x16x32_bf16 v[58:61], v[192:195], v[152:155], v[58:61]
	v_mfma_f32_16x16x32_bf16 v[54:57], v[192:195], v[156:159], v[54:57]
	v_mfma_f32_16x16x32_bf16 v[50:53], v[192:195], v[162:165], v[50:53]
	v_mfma_f32_16x16x32_bf16 v[46:49], v[192:195], v[166:169], v[46:49]
	v_mfma_f32_16x16x32_bf16 v[42:45], v[192:195], v[170:173], v[42:45]
	v_mfma_f32_16x16x32_bf16 v[38:41], v[192:195], v[176:179], v[38:41]
	v_mfma_f32_16x16x32_bf16 v[34:37], v[192:195], v[180:183], v[34:37]
	v_mfma_f32_16x16x32_bf16 v[30:33], v[196:199], v[146:149], v[30:33]
	v_mfma_f32_16x16x32_bf16 v[26:29], v[196:199], v[152:155], v[26:29]
	v_mfma_f32_16x16x32_bf16 v[22:25], v[196:199], v[156:159], v[22:25]
	v_mfma_f32_16x16x32_bf16 v[18:21], v[196:199], v[162:165], v[18:21]
	v_mfma_f32_16x16x32_bf16 v[14:17], v[196:199], v[166:169], v[14:17]
	v_mfma_f32_16x16x32_bf16 v[10:13], v[196:199], v[170:173], v[10:13]
	v_mfma_f32_16x16x32_bf16 v[6:9], v[196:199], v[176:179], v[6:9]
	v_mfma_f32_16x16x32_bf16 v[2:5], v[196:199], v[180:183], v[2:5]
	s_mov_b32 s37, s36
	s_add_i32 s36, s36, 0x6000
	s_cmp_eq_u32 s36, 0x12000
	s_cselect_b32 s36, 0, s36
	s_waitcnt lgkmcnt(0)
	v_mfma_f32_16x16x32_bf16 v[126:129], v[232:235], v[200:203], v[126:129]
	v_mfma_f32_16x16x32_bf16 v[122:125], v[232:235], v[204:207], v[122:125]
	v_mfma_f32_16x16x32_bf16 v[118:121], v[232:235], v[208:211], v[118:121]
	v_mfma_f32_16x16x32_bf16 v[114:117], v[232:235], v[212:215], v[114:117]
	v_mfma_f32_16x16x32_bf16 v[110:113], v[232:235], v[216:219], v[110:113]
	v_mfma_f32_16x16x32_bf16 v[106:109], v[232:235], v[220:223], v[106:109]
	v_mfma_f32_16x16x32_bf16 v[102:105], v[232:235], v[224:227], v[102:105]
	v_mfma_f32_16x16x32_bf16 v[98:101], v[232:235], v[228:231], v[98:101]
	v_mfma_f32_16x16x32_bf16 v[94:97], v[236:239], v[200:203], v[94:97]
	v_mfma_f32_16x16x32_bf16 v[90:93], v[236:239], v[204:207], v[90:93]
	v_mfma_f32_16x16x32_bf16 v[86:89], v[236:239], v[208:211], v[86:89]
	v_mfma_f32_16x16x32_bf16 v[82:85], v[236:239], v[212:215], v[82:85]
	v_mfma_f32_16x16x32_bf16 v[78:81], v[236:239], v[216:219], v[78:81]
	v_mfma_f32_16x16x32_bf16 v[74:77], v[236:239], v[220:223], v[74:77]
	v_mfma_f32_16x16x32_bf16 v[70:73], v[236:239], v[224:227], v[70:73]
	v_mfma_f32_16x16x32_bf16 v[66:69], v[236:239], v[228:231], v[66:69]
	v_mfma_f32_16x16x32_bf16 v[62:65], v[240:243], v[200:203], v[62:65]
	v_mfma_f32_16x16x32_bf16 v[58:61], v[240:243], v[204:207], v[58:61]
	v_mfma_f32_16x16x32_bf16 v[54:57], v[240:243], v[208:211], v[54:57]
	v_mfma_f32_16x16x32_bf16 v[50:53], v[240:243], v[212:215], v[50:53]
	v_mfma_f32_16x16x32_bf16 v[46:49], v[240:243], v[216:219], v[46:49]
	v_mfma_f32_16x16x32_bf16 v[42:45], v[240:243], v[220:223], v[42:45]
	v_mfma_f32_16x16x32_bf16 v[38:41], v[240:243], v[224:227], v[38:41]
	v_mfma_f32_16x16x32_bf16 v[34:37], v[240:243], v[228:231], v[34:37]
	v_mfma_f32_16x16x32_bf16 v[30:33], v[244:247], v[200:203], v[30:33]
	v_mfma_f32_16x16x32_bf16 v[26:29], v[244:247], v[204:207], v[26:29]
	v_mfma_f32_16x16x32_bf16 v[22:25], v[244:247], v[208:211], v[22:25]
	v_mfma_f32_16x16x32_bf16 v[18:21], v[244:247], v[212:215], v[18:21]
	v_mfma_f32_16x16x32_bf16 v[14:17], v[244:247], v[216:219], v[14:17]
	v_mfma_f32_16x16x32_bf16 v[10:13], v[244:247], v[220:223], v[10:13]
	v_mfma_f32_16x16x32_bf16 v[6:9], v[244:247], v[224:227], v[6:9]
	v_mfma_f32_16x16x32_bf16 v[2:5], v[244:247], v[228:231], v[2:5]
	s_mov_b32 m0, s39
	s_mov_b32 s10, 0x16000
	s_mov_b32 s11, 0
	s_mov_b32 s40, 0xbfb8aa3b
	s_nop 7
	v_mul_f32_e32 v216, s40, v126
	v_mul_f32_e32 v217, s40, v127
	v_mul_f32_e32 v218, s40, v128
	v_mul_f32_e32 v219, s40, v129
	v_exp_f32_e32 v216, v216
	v_exp_f32_e32 v217, v217
	v_exp_f32_e32 v218, v218
	v_exp_f32_e32 v219, v219
	v_add_f32_e32 v216, 1.0, v216
	v_add_f32_e32 v217, 1.0, v217
	v_add_f32_e32 v218, 1.0, v218
	v_add_f32_e32 v219, 1.0, v219
	v_rcp_f32_e32 v216, v216
; DEVI unsigned pack2(float a, float b) { return __builtin_bit_cast(unsigned, __builtin_convertvector((f32x2_t){a, b}, bf16x2_t)); }
; DEVI float sigmoidf_(float x) { return __builtin_amdgcn_rcpf(1.f + __expf(-x)); }
; DEVI float siluf_(float x) { return x * __builtin_amdgcn_rcpf(1.f + __expf(-x)); }
;     ...
;     if (EPI == EPI_SWIGLU) {
; #pragma unroll
;       for (int nf = 0; nf < 2; nf++) {
;         const int hcol = (n0 >> 1) + wn * 32 + nf * 16 + quad * 4;
;         f32x4 g = acc[nf][mf], u = acc[nf + 2][mf];
;         u32x2 pk;
;         pk[0] = pack2(siluf_(g[0]) * u[0], siluf_(g[1]) * u[1]);
;         pk[1] = pack2(siluf_(g[2]) * u[2], siluf_(g[3]) * u[3]);
;         *(u32x2*)(outb + (size_t)row * DFF + hcol) = pk;
;       }
	v_rcp_f32_e32 v217, v217
	v_rcp_f32_e32 v218, v218
	v_rcp_f32_e32 v219, v219
	v_mul_f32_e32 v126, v126, v216
	v_mul_f32_e32 v127, v127, v217
	v_mul_f32_e32 v128, v128, v218
	v_mul_f32_e32 v129, v129, v219
	v_mul_f32_e32 v126, v126, v62
	v_mul_f32_e32 v127, v127, v63
	v_mul_f32_e32 v128, v128, v64
	v_mul_f32_e32 v129, v129, v65
	v_mul_f32_e32 v220, s40, v94
	v_mul_f32_e32 v221, s40, v95
	v_mul_f32_e32 v222, s40, v96
	v_mul_f32_e32 v223, s40, v97
	v_exp_f32_e32 v220, v220
	v_exp_f32_e32 v221, v221
	v_exp_f32_e32 v222, v222
	v_exp_f32_e32 v223, v223
	v_add_f32_e32 v220, 1.0, v220
	v_add_f32_e32 v221, 1.0, v221
	v_add_f32_e32 v222, 1.0, v222
	v_add_f32_e32 v223, 1.0, v223
	v_rcp_f32_e32 v220, v220
	v_rcp_f32_e32 v221, v221
	v_rcp_f32_e32 v222, v222
	v_rcp_f32_e32 v223, v223
	v_mul_f32_e32 v94, v94, v220
	v_mul_f32_e32 v95, v95, v221
	v_mul_f32_e32 v96, v96, v222
	v_mul_f32_e32 v97, v97, v223
	v_mul_f32_e32 v94, v94, v30
	v_mul_f32_e32 v95, v95, v31
	v_mul_f32_e32 v96, v96, v32
	v_mul_f32_e32 v97, v97, v33
	v_cvt_pk_bf16_f32 v126, v126, v127
	v_cvt_pk_bf16_f32 v127, v128, v129
	v_cvt_pk_bf16_f32 v128, v94, v95
	v_cvt_pk_bf16_f32 v129, v96, v97
	s_nop 1
	v_permlane16_swap_b32_e32 v126, v128
	v_permlane16_swap_b32_e32 v127, v129
	global_store_dwordx4 v[140:141], v[126:129], off
	v_lshl_add_u64 v[140:141], v[140:141], 0, s[10:11]
	v_mul_f32_e32 v216, s40, v122
	v_mul_f32_e32 v217, s40, v123
	v_mul_f32_e32 v218, s40, v124
	v_mul_f32_e32 v219, s40, v125
	v_exp_f32_e32 v216, v216
	v_exp_f32_e32 v217, v217
	v_exp_f32_e32 v218, v218
	v_exp_f32_e32 v219, v219
	v_add_f32_e32 v216, 1.0, v216
	v_add_f32_e32 v217, 1.0, v217
	v_add_f32_e32 v218, 1.0, v218
	v_add_f32_e32 v219, 1.0, v219
	v_rcp_f32_e32 v216, v216
	v_rcp_f32_e32 v217, v217
	v_rcp_f32_e32 v218, v218
	v_rcp_f32_e32 v219, v219
	v_mul_f32_e32 v122, v122, v216
	v_mul_f32_e32 v123, v123, v217
	v_mul_f32_e32 v124, v124, v218
	v_mul_f32_e32 v125, v125, v219
	v_mul_f32_e32 v122, v122, v58
	v_mul_f32_e32 v123, v123, v59
	v_mul_f32_e32 v124, v124, v60
	v_mul_f32_e32 v125, v125, v61
	v_mul_f32_e32 v220, s40, v90
	v_mul_f32_e32 v221, s40, v91
	v_mul_f32_e32 v222, s40, v92
	v_mul_f32_e32 v223, s40, v93
	v_exp_f32_e32 v220, v220
	v_exp_f32_e32 v221, v221
	v_exp_f32_e32 v222, v222
	v_exp_f32_e32 v223, v223
	v_add_f32_e32 v220, 1.0, v220
	v_add_f32_e32 v221, 1.0, v221
	v_add_f32_e32 v222, 1.0, v222
	v_add_f32_e32 v223, 1.0, v223
	v_rcp_f32_e32 v220, v220
	v_rcp_f32_e32 v221, v221
	v_rcp_f32_e32 v222, v222
	v_rcp_f32_e32 v223, v223
	v_mul_f32_e32 v90, v90, v220
	v_mul_f32_e32 v91, v91, v221
	v_mul_f32_e32 v92, v92, v222
	v_mul_f32_e32 v93, v93, v223
	v_mul_f32_e32 v90, v90, v26
	v_mul_f32_e32 v91, v91, v27
	v_mul_f32_e32 v92, v92, v28
	v_mul_f32_e32 v93, v93, v29
	v_cvt_pk_bf16_f32 v122, v122, v123
	v_cvt_pk_bf16_f32 v123, v124, v125
	v_cvt_pk_bf16_f32 v124, v90, v91
	v_cvt_pk_bf16_f32 v125, v92, v93
	s_nop 1
	v_permlane16_swap_b32_e32 v122, v124
	v_permlane16_swap_b32_e32 v123, v125
	global_store_dwordx4 v[140:141], v[122:125], off
	v_lshl_add_u64 v[140:141], v[140:141], 0, s[10:11]
	v_mul_f32_e32 v216, s40, v118
	v_mul_f32_e32 v217, s40, v119
	v_mul_f32_e32 v218, s40, v120
	v_mul_f32_e32 v219, s40, v121
	v_exp_f32_e32 v216, v216
	v_exp_f32_e32 v217, v217
	v_exp_f32_e32 v218, v218
	v_exp_f32_e32 v219, v219
	v_add_f32_e32 v216, 1.0, v216
	v_add_f32_e32 v217, 1.0, v217
	v_add_f32_e32 v218, 1.0, v218
	v_add_f32_e32 v219, 1.0, v219
	v_rcp_f32_e32 v216, v216
	v_rcp_f32_e32 v217, v217
	v_rcp_f32_e32 v218, v218
	v_rcp_f32_e32 v219, v219
	v_mul_f32_e32 v118, v118, v216
	v_mul_f32_e32 v119, v119, v217
	v_mul_f32_e32 v120, v120, v218
	v_mul_f32_e32 v121, v121, v219
	v_mul_f32_e32 v118, v118, v54
	v_mul_f32_e32 v119, v119, v55
	v_mul_f32_e32 v120, v120, v56
	v_mul_f32_e32 v121, v121, v57
	v_mul_f32_e32 v220, s40, v86
	v_mul_f32_e32 v221, s40, v87
	v_mul_f32_e32 v222, s40, v88
	v_mul_f32_e32 v223, s40, v89
	v_exp_f32_e32 v220, v220
	v_exp_f32_e32 v221, v221
	v_exp_f32_e32 v222, v222
	v_exp_f32_e32 v223, v223
	v_add_f32_e32 v220, 1.0, v220
	v_add_f32_e32 v221, 1.0, v221
	v_add_f32_e32 v222, 1.0, v222
	v_add_f32_e32 v223, 1.0, v223
	v_rcp_f32_e32 v220, v220
	v_rcp_f32_e32 v221, v221
	v_rcp_f32_e32 v222, v222
	v_rcp_f32_e32 v223, v223
	v_mul_f32_e32 v86, v86, v220
	v_mul_f32_e32 v87, v87, v221
	v_mul_f32_e32 v88, v88, v222
	v_mul_f32_e32 v89, v89, v223
	v_mul_f32_e32 v86, v86, v22
	v_mul_f32_e32 v87, v87, v23
	v_mul_f32_e32 v88, v88, v24
	v_mul_f32_e32 v89, v89, v25
	v_cvt_pk_bf16_f32 v118, v118, v119
	v_cvt_pk_bf16_f32 v119, v120, v121
	v_cvt_pk_bf16_f32 v120, v86, v87
	v_cvt_pk_bf16_f32 v121, v88, v89
	s_nop 1
	v_permlane16_swap_b32_e32 v118, v120
	v_permlane16_swap_b32_e32 v119, v121
	global_store_dwordx4 v[140:141], v[118:121], off
	v_lshl_add_u64 v[140:141], v[140:141], 0, s[10:11]
	v_mul_f32_e32 v216, s40, v114
	v_mul_f32_e32 v217, s40, v115
	v_mul_f32_e32 v218, s40, v116
	v_mul_f32_e32 v219, s40, v117
	v_exp_f32_e32 v216, v216
	v_exp_f32_e32 v217, v217
	v_exp_f32_e32 v218, v218
	v_exp_f32_e32 v219, v219
	v_add_f32_e32 v216, 1.0, v216
	v_add_f32_e32 v217, 1.0, v217
	v_add_f32_e32 v218, 1.0, v218
	v_add_f32_e32 v219, 1.0, v219
	v_rcp_f32_e32 v216, v216
	v_rcp_f32_e32 v217, v217
	v_rcp_f32_e32 v218, v218
	v_rcp_f32_e32 v219, v219
	v_mul_f32_e32 v114, v114, v216
	v_mul_f32_e32 v115, v115, v217
	v_mul_f32_e32 v116, v116, v218
	v_mul_f32_e32 v117, v117, v219
	v_mul_f32_e32 v114, v114, v50
	v_mul_f32_e32 v115, v115, v51
	v_mul_f32_e32 v116, v116, v52
	v_mul_f32_e32 v117, v117, v53
	v_mul_f32_e32 v220, s40, v82
	v_mul_f32_e32 v221, s40, v83
	v_mul_f32_e32 v222, s40, v84
	v_mul_f32_e32 v223, s40, v85
	v_exp_f32_e32 v220, v220
; DEVI unsigned pack2(float a, float b) { return __builtin_bit_cast(unsigned, __builtin_convertvector((f32x2_t){a, b}, bf16x2_t)); }
; DEVI float sigmoidf_(float x) { return __builtin_amdgcn_rcpf(1.f + __expf(-x)); }
; DEVI float siluf_(float x) { return x * __builtin_amdgcn_rcpf(1.f + __expf(-x)); }
;     ...
;     if (EPI == EPI_SWIGLU) {
; #pragma unroll
;       for (int nf = 0; nf < 2; nf++) {
;         const int hcol = (n0 >> 1) + wn * 32 + nf * 16 + quad * 4;
;         f32x4 g = acc[nf][mf], u = acc[nf + 2][mf];
;         u32x2 pk;
;         pk[0] = pack2(siluf_(g[0]) * u[0], siluf_(g[1]) * u[1]);
;         pk[1] = pack2(siluf_(g[2]) * u[2], siluf_(g[3]) * u[3]);
;         *(u32x2*)(outb + (size_t)row * DFF + hcol) = pk;
;       }
	v_exp_f32_e32 v221, v221
	v_exp_f32_e32 v222, v222
	v_exp_f32_e32 v223, v223
	v_add_f32_e32 v220, 1.0, v220
	v_add_f32_e32 v221, 1.0, v221
	v_add_f32_e32 v222, 1.0, v222
	v_add_f32_e32 v223, 1.0, v223
	v_rcp_f32_e32 v220, v220
	v_rcp_f32_e32 v221, v221
	v_rcp_f32_e32 v222, v222
	v_rcp_f32_e32 v223, v223
	v_mul_f32_e32 v82, v82, v220
	v_mul_f32_e32 v83, v83, v221
	v_mul_f32_e32 v84, v84, v222
	v_mul_f32_e32 v85, v85, v223
	v_mul_f32_e32 v82, v82, v18
	v_mul_f32_e32 v83, v83, v19
	v_mul_f32_e32 v84, v84, v20
	v_mul_f32_e32 v85, v85, v21
	v_cvt_pk_bf16_f32 v114, v114, v115
	v_cvt_pk_bf16_f32 v115, v116, v117
	v_cvt_pk_bf16_f32 v116, v82, v83
	v_cvt_pk_bf16_f32 v117, v84, v85
	s_nop 1
	v_permlane16_swap_b32_e32 v114, v116
	v_permlane16_swap_b32_e32 v115, v117
	global_store_dwordx4 v[140:141], v[114:117], off
	v_lshl_add_u64 v[140:141], v[140:141], 0, s[10:11]
	v_mul_f32_e32 v216, s40, v110
	v_mul_f32_e32 v217, s40, v111
	v_mul_f32_e32 v218, s40, v112
	v_mul_f32_e32 v219, s40, v113
	v_exp_f32_e32 v216, v216
	v_exp_f32_e32 v217, v217
	v_exp_f32_e32 v218, v218
	v_exp_f32_e32 v219, v219
	v_add_f32_e32 v216, 1.0, v216
	v_add_f32_e32 v217, 1.0, v217
	v_add_f32_e32 v218, 1.0, v218
	v_add_f32_e32 v219, 1.0, v219
	v_rcp_f32_e32 v216, v216
	v_rcp_f32_e32 v217, v217
	v_rcp_f32_e32 v218, v218
	v_rcp_f32_e32 v219, v219
	v_mul_f32_e32 v110, v110, v216
	v_mul_f32_e32 v111, v111, v217
	v_mul_f32_e32 v112, v112, v218
	v_mul_f32_e32 v113, v113, v219
	v_mul_f32_e32 v110, v110, v46
	v_mul_f32_e32 v111, v111, v47
	v_mul_f32_e32 v112, v112, v48
	v_mul_f32_e32 v113, v113, v49
	v_mul_f32_e32 v220, s40, v78
	v_mul_f32_e32 v221, s40, v79
	v_mul_f32_e32 v222, s40, v80
	v_mul_f32_e32 v223, s40, v81
	v_exp_f32_e32 v220, v220
	v_exp_f32_e32 v221, v221
	v_exp_f32_e32 v222, v222
	v_exp_f32_e32 v223, v223
	v_add_f32_e32 v220, 1.0, v220
	v_add_f32_e32 v221, 1.0, v221
	v_add_f32_e32 v222, 1.0, v222
	v_add_f32_e32 v223, 1.0, v223
	v_rcp_f32_e32 v220, v220
	v_rcp_f32_e32 v221, v221
	v_rcp_f32_e32 v222, v222
	v_rcp_f32_e32 v223, v223
	v_mul_f32_e32 v78, v78, v220
	v_mul_f32_e32 v79, v79, v221
	v_mul_f32_e32 v80, v80, v222
	v_mul_f32_e32 v81, v81, v223
	v_mul_f32_e32 v78, v78, v14
	v_mul_f32_e32 v79, v79, v15
	v_mul_f32_e32 v80, v80, v16
	v_mul_f32_e32 v81, v81, v17
	v_cvt_pk_bf16_f32 v110, v110, v111
	v_cvt_pk_bf16_f32 v111, v112, v113
	v_cvt_pk_bf16_f32 v112, v78, v79
	v_cvt_pk_bf16_f32 v113, v80, v81
	s_nop 1
	v_permlane16_swap_b32_e32 v110, v112
	v_permlane16_swap_b32_e32 v111, v113
	global_store_dwordx4 v[140:141], v[110:113], off
	v_lshl_add_u64 v[140:141], v[140:141], 0, s[10:11]
	v_mul_f32_e32 v216, s40, v106
	v_mul_f32_e32 v217, s40, v107
	v_mul_f32_e32 v218, s40, v108
	v_mul_f32_e32 v219, s40, v109
	v_exp_f32_e32 v216, v216
	v_exp_f32_e32 v217, v217
	v_exp_f32_e32 v218, v218
	v_exp_f32_e32 v219, v219
	v_add_f32_e32 v216, 1.0, v216
	v_add_f32_e32 v217, 1.0, v217
	v_add_f32_e32 v218, 1.0, v218
	v_add_f32_e32 v219, 1.0, v219
	v_rcp_f32_e32 v216, v216
	v_rcp_f32_e32 v217, v217
	v_rcp_f32_e32 v218, v218
	v_rcp_f32_e32 v219, v219
	v_mul_f32_e32 v106, v106, v216
	v_mul_f32_e32 v107, v107, v217
	v_mul_f32_e32 v108, v108, v218
	v_mul_f32_e32 v109, v109, v219
	v_mul_f32_e32 v106, v106, v42
	v_mul_f32_e32 v107, v107, v43
	v_mul_f32_e32 v108, v108, v44
	v_mul_f32_e32 v109, v109, v45
	v_mul_f32_e32 v220, s40, v74
	v_mul_f32_e32 v221, s40, v75
	v_mul_f32_e32 v222, s40, v76
	v_mul_f32_e32 v223, s40, v77
	v_exp_f32_e32 v220, v220
	v_exp_f32_e32 v221, v221
	v_exp_f32_e32 v222, v222
	v_exp_f32_e32 v223, v223
	v_add_f32_e32 v220, 1.0, v220
	v_add_f32_e32 v221, 1.0, v221
	v_add_f32_e32 v222, 1.0, v222
	v_add_f32_e32 v223, 1.0, v223
	v_rcp_f32_e32 v220, v220
	v_rcp_f32_e32 v221, v221
	v_rcp_f32_e32 v222, v222
	v_rcp_f32_e32 v223, v223
	v_mul_f32_e32 v74, v74, v220
	v_mul_f32_e32 v75, v75, v221
	v_mul_f32_e32 v76, v76, v222
	v_mul_f32_e32 v77, v77, v223
	v_mul_f32_e32 v74, v74, v10
; DEVI unsigned pack2(float a, float b) { return __builtin_bit_cast(unsigned, __builtin_convertvector((f32x2_t){a, b}, bf16x2_t)); }
; DEVI float siluf_(float x) { return x * __builtin_amdgcn_rcpf(1.f + __expf(-x)); }
; DEVI int xcd_first_tile() { return (blockIdx.x & 7) * (gridDim.x >> 3) + (blockIdx.x >> 3); }
;     ...
;     if (EPI == EPI_SWIGLU) {
; #pragma unroll
;       for (int nf = 0; nf < 2; nf++) {
;         const int hcol = (n0 >> 1) + wn * 32 + nf * 16 + quad * 4;
;         f32x4 g = acc[nf][mf], u = acc[nf + 2][mf];
;         u32x2 pk;
;         pk[0] = pack2(siluf_(g[0]) * u[0], siluf_(g[1]) * u[1]);
;         pk[1] = pack2(siluf_(g[2]) * u[2], siluf_(g[3]) * u[3]);
;         *(u32x2*)(outb + (size_t)row * DFF + hcol) = pk;
;       }
; DEVI void run_phase(const Params& p, int ph, char* smem) {
;     ...
;       for (int t = xcd_first_tile(); t < 66 * 44; t += xcd_tile_step()) {
	v_mul_f32_e32 v75, v75, v11
	v_mul_f32_e32 v76, v76, v12
	v_mul_f32_e32 v77, v77, v13
	v_cvt_pk_bf16_f32 v106, v106, v107
	v_cvt_pk_bf16_f32 v107, v108, v109
	v_cvt_pk_bf16_f32 v108, v74, v75
	v_cvt_pk_bf16_f32 v109, v76, v77
	s_nop 1
	v_permlane16_swap_b32_e32 v106, v108
	v_permlane16_swap_b32_e32 v107, v109
	global_store_dwordx4 v[140:141], v[106:109], off
	v_lshl_add_u64 v[140:141], v[140:141], 0, s[10:11]
	v_mul_f32_e32 v216, s40, v102
	v_mul_f32_e32 v217, s40, v103
	v_mul_f32_e32 v218, s40, v104
	v_mul_f32_e32 v219, s40, v105
	v_exp_f32_e32 v216, v216
	v_exp_f32_e32 v217, v217
	v_exp_f32_e32 v218, v218
	v_exp_f32_e32 v219, v219
	v_add_f32_e32 v216, 1.0, v216
	v_add_f32_e32 v217, 1.0, v217
	v_add_f32_e32 v218, 1.0, v218
	v_add_f32_e32 v219, 1.0, v219
	v_rcp_f32_e32 v216, v216
	v_rcp_f32_e32 v217, v217
	v_rcp_f32_e32 v218, v218
	v_rcp_f32_e32 v219, v219
	v_mul_f32_e32 v102, v102, v216
	v_mul_f32_e32 v103, v103, v217
	v_mul_f32_e32 v104, v104, v218
	v_mul_f32_e32 v105, v105, v219
	v_mul_f32_e32 v102, v102, v38
	v_mul_f32_e32 v103, v103, v39
	v_mul_f32_e32 v104, v104, v40
	v_mul_f32_e32 v105, v105, v41
	v_mul_f32_e32 v220, s40, v70
	v_mul_f32_e32 v221, s40, v71
	v_mul_f32_e32 v222, s40, v72
	v_mul_f32_e32 v223, s40, v73
	v_exp_f32_e32 v220, v220
	v_exp_f32_e32 v221, v221
	v_exp_f32_e32 v222, v222
	v_exp_f32_e32 v223, v223
	v_add_f32_e32 v220, 1.0, v220
	v_add_f32_e32 v221, 1.0, v221
	v_add_f32_e32 v222, 1.0, v222
	v_add_f32_e32 v223, 1.0, v223
	v_rcp_f32_e32 v220, v220
	v_rcp_f32_e32 v221, v221
	v_rcp_f32_e32 v222, v222
	v_rcp_f32_e32 v223, v223
	v_mul_f32_e32 v70, v70, v220
	v_mul_f32_e32 v71, v71, v221
	v_mul_f32_e32 v72, v72, v222
	v_mul_f32_e32 v73, v73, v223
	v_mul_f32_e32 v70, v70, v6
	v_mul_f32_e32 v71, v71, v7
	v_mul_f32_e32 v72, v72, v8
	v_mul_f32_e32 v73, v73, v9
	v_cvt_pk_bf16_f32 v102, v102, v103
	v_cvt_pk_bf16_f32 v103, v104, v105
	v_cvt_pk_bf16_f32 v104, v70, v71
	v_cvt_pk_bf16_f32 v105, v72, v73
	s_nop 1
	v_permlane16_swap_b32_e32 v102, v104
	v_permlane16_swap_b32_e32 v103, v105
	global_store_dwordx4 v[140:141], v[102:105], off
	v_lshl_add_u64 v[140:141], v[140:141], 0, s[10:11]
	v_mul_f32_e32 v216, s40, v98
	v_mul_f32_e32 v217, s40, v99
	v_mul_f32_e32 v218, s40, v100
	v_mul_f32_e32 v219, s40, v101
	v_exp_f32_e32 v216, v216
	v_exp_f32_e32 v217, v217
	v_exp_f32_e32 v218, v218
	v_exp_f32_e32 v219, v219
	v_add_f32_e32 v216, 1.0, v216
	v_add_f32_e32 v217, 1.0, v217
	v_add_f32_e32 v218, 1.0, v218
	v_add_f32_e32 v219, 1.0, v219
	v_rcp_f32_e32 v216, v216
	v_rcp_f32_e32 v217, v217
	v_rcp_f32_e32 v218, v218
	v_rcp_f32_e32 v219, v219
	v_mul_f32_e32 v98, v98, v216
	v_mul_f32_e32 v99, v99, v217
	v_mul_f32_e32 v100, v100, v218
	v_mul_f32_e32 v101, v101, v219
	v_mul_f32_e32 v98, v98, v34
	v_mul_f32_e32 v99, v99, v35
	v_mul_f32_e32 v100, v100, v36
	v_mul_f32_e32 v101, v101, v37
	v_mul_f32_e32 v220, s40, v66
	v_mul_f32_e32 v221, s40, v67
	v_mul_f32_e32 v222, s40, v68
	v_mul_f32_e32 v223, s40, v69
	v_exp_f32_e32 v220, v220
	v_exp_f32_e32 v221, v221
	v_exp_f32_e32 v222, v222
	v_exp_f32_e32 v223, v223
	v_add_f32_e32 v220, 1.0, v220
	v_add_f32_e32 v221, 1.0, v221
	v_add_f32_e32 v222, 1.0, v222
	v_add_f32_e32 v223, 1.0, v223
	v_rcp_f32_e32 v220, v220
	v_rcp_f32_e32 v221, v221
	v_rcp_f32_e32 v222, v222
	v_rcp_f32_e32 v223, v223
	v_mul_f32_e32 v66, v66, v220
	v_mul_f32_e32 v67, v67, v221
	v_mul_f32_e32 v68, v68, v222
	v_mul_f32_e32 v69, v69, v223
	v_mul_f32_e32 v66, v66, v2
	v_mul_f32_e32 v67, v67, v3
	v_mul_f32_e32 v68, v68, v4
	v_mul_f32_e32 v69, v69, v5
	v_cvt_pk_bf16_f32 v98, v98, v99
	v_cvt_pk_bf16_f32 v99, v100, v101
	v_cvt_pk_bf16_f32 v100, v66, v67
	v_cvt_pk_bf16_f32 v101, v68, v69
	s_nop 1
	v_permlane16_swap_b32_e32 v98, v100
	v_permlane16_swap_b32_e32 v99, v101
	global_store_dwordx4 v[140:141], v[98:101], off
	v_readlane_b32 s42, v250, 7
	s_add_i32 s8, s8, s42
	s_cmpk_gt_i32 s8, 0xb57
	s_cbranch_scc0 .LBB0_124
	s_branch .LBB0_131

; #define LAS __attribute__((address_space(3)))
; DEVI int tidx() { int t = threadIdx.x; asm volatile("" : "+v"(t)); return t; }
; DEVI unsigned pack2(float a, float b) { return __builtin_bit_cast(unsigned, __builtin_convertvector((f32x2_t){a, b}, bf16x2_t)); }
; DEVI float blo(unsigned u) { return __uint_as_float(u << 16); }
; DEVI float bhi(unsigned u) { return __uint_as_float(u & 0xffff0000u); }
;   const int tid = tidx(), lane = tid & 63, wid = tid >> 6;
;   const int wm = wid >> 1, wn = wid & 1, r16 = lane & 15, quad = lane >> 4;
;   f32x4 acc[4][8];
; #pragma unroll
;   for (int i = 0; i < 4; i++)
; #pragma unroll
;     for (int j = 0; j < 8; j++) acc[i][j] = (f32x4){0.f, 0.f, 0.f, 0.f};
;   const int nk = (nk_part < 0) ? (K >> 5) : nk_part;
;   const int lrow = tid >> 2, lpc = tid & 3;
;   const int lch = lpc ^ ((0x78 >> (((lrow >> 2) & 3) * 2)) & 3);
;   const u16* ga = A + (size_t)(m0 + lrow) * lda + kbeg + lch * 8;
;   const u16* gb = Bt + (size_t)(n0 + lrow) * K + kbeg + lch * 8;
;   const size_t ga1 = (size_t)64 * lda, gb1 = (size_t)64 * K;
;   const unsigned lds0 = (unsigned)(uintptr_t)(LAS char*)smem + (unsigned)__builtin_amdgcn_readfirstlane(wid) * 1024u;
;     ...
;   __syncthreads();
;   G2_STAGE(0); G2_STAGE(1);
;   const int fsw = (0x78 >> (((r16 >> 2) & 3) * 2)) & 3;
;   const int aoff = (wm * 128 + r16) * 64 + ((quad ^ fsw) << 4);
;   const int boff = 16384 + (wn * 64 + r16) * 64 + ((quad ^ fsw) << 4);
;     ...
;         const int col = n0 + wn * 64 + nf * 16 + quad * 4;
;         f32x4 a = acc[nf][mf];
;         if (EPI == EPI_RESID || EPI == EPI_RESID_ATOMIC) {
;           f32x4 x = a;
;           if (EPI == EPI_RESID || kpart == 0) {
;             const u32x2 xr = *(const u32x2*)((const u16*)(p.ws + WS_XB) + (size_t)row * 1024 + col);
;             x[0] += ALPHA * blo(xr[0]); x[1] += ALPHA * bhi(xr[0]); x[2] += ALPHA * blo(xr[1]); x[3] += ALPHA * bhi(xr[1]);
;           }
;           if (EPI == EPI_RESID) *(f32x4*)((float*)(p.ws + WS_XF) + (size_t)row * 1024 + col) = x;
;           else *(f32x4*)((float*)(p.ws + WS_SLAB) + ((size_t)kpart * 512 + (row - T_P)) * 1024 + col) = x;
;         } else {
;           u32x2 pk; pk[0] = pack2(a[0], a[1]); pk[1] = pack2(a[2], a[3]);
;           *(u32x2*)(outb + (size_t)row * ldc + col) = pk;
.Lt0_crd:
	s_cmp_lt_u32 s43, 64
	s_cselect_b32 s42, 1, 0
	v_readlane_b32 s2, v250, 5
	v_readlane_b32 s3, v250, 6
	v_readlane_b32 s44, v254, 62
	s_mul_i32 s38, s43, 0x80000
	s_add_u32 s8, s2, s38
	s_addc_u32 s9, s3, 0
	s_add_u32 s8, s8, 0x4200000
	s_addc_u32 s9, s9, 0
	s_mul_i32 s38, s44, 0x500000
	s_mul_i32 s39, s40, 0x40000
	s_add_i32 s38, s38, s39
	s_add_u32 s10, s2, s38
	s_addc_u32 s11, s3, 0
	s_add_u32 s10, s10, 0x14a00000
	s_addc_u32 s11, s11, 0
	s_movk_i32 s15, 0x78
	v_lshrrev_b32_e32 v0, 2, v145
	v_and_b32_e32 v131, 3, v145
	v_bfe_u32 v136, v145, 4, 2
	v_lshlrev_b32_e32 v136, 1, v136
	v_lshrrev_b32_e64 v136, v136, s15
	v_and_b32_e32 v136, 3, v136
	v_xor_b32_e32 v131, v131, v136
	v_lshlrev_b32_e32 v131, 4, v131
	s_movk_i32 s39, 0x800
	v_mad_u32_u24 v0, v0, s39, v131
	v_bfe_u32 v137, v145, 2, 1
	s_movk_i32 s39, 0x7c0
	v_mul_u32_u24_e32 v136, s39, v137
	v_sub_u32_e32 v136, v0, v136
	v_mov_b32_e32 v137, 0
	v_lshl_add_u64 v[134:135], s[10:11], 0, v[136:137]
	v_bfe_u32 v137, v145, 2, 1
	s_mul_i32 s39, s42, 0x7c0
	v_mul_u32_u24_e32 v136, s39, v137
	v_sub_u32_e32 v0, v0, v136
	s_lshl_b32 s36, s42, 6
	s_add_i32 s36, s36, 64
	s_mov_b32 s37, 0
	v_lshl_add_u64 v[132:133], s[8:9], 0, v[0:1]
	v_bfe_u32 v136, v145, 2, 2
	v_lshlrev_b32_e32 v136, 1, v136
	v_lshrrev_b32_e64 v136, v136, s15
	v_and_b32_e32 v136, 3, v136
	v_bfe_u32 v137, v145, 4, 2
	v_xor_b32_e32 v136, v136, v137
	v_lshlrev_b32_e32 v136, 4, v136
	v_and_b32_e32 v131, 15, v145
	v_lshl_or_b32 v136, v131, 6, v136
	v_bfe_u32 v137, v145, 6, 1
	v_lshl_or_b32 v137, v137, 12, v136
	v_lshrrev_b32_e32 v0, 7, v145
	v_lshl_or_b32 v136, v0, 13, v136
	v_and_b32_e32 v140, 1, v131
	v_lshl_or_b32 v131, v0, 7, v131
	v_bfe_u32 v0, v145, 4, 1
	v_lshlrev_b32_e32 v0, 5, v0
	v_bfe_u32 v141, v145, 5, 1
	v_lshl_or_b32 v0, v141, 4, v0
	v_bfe_u32 v141, v145, 6, 1
	s_mul_i32 s38, s43, 0x140000
	s_lshl_b32 s39, s40, 8
	s_add_i32 s38, s38, s39
	s_add_u32 s10, s2, s38
	s_addc_u32 s11, s3, 0
	s_add_u32 s10, s10, 0x6300000
	s_addc_u32 s11, s11, 0
	s_movk_i32 s39, 5120
	v_mad_u32_u24 v138, v131, s39, v0
	v_lshl_add_u32 v138, v141, 7, v138
	v_mov_b32_e32 v139, 0
	v_lshl_add_u64 v[140:141], s[10:11], 0, v[138:139]
	s_mov_b32 s2, 0x20000
	s_mov_b32 s3, 0
	v_lshrrev_b32_e32 v0, 6, v145
	v_lshlrev_b32_e32 v0, 10, v0
	s_nop 0
	v_readfirstlane_b32 s44, v0
	s_mov_b32 s41, m0
	s_mov_b32 s8, 128
	s_mov_b32 s9, 0
	v_mov_b32_e32 v2, 0
	v_mov_b32_e32 v3, 0
	v_mov_b32_e32 v4, 0
	v_mov_b32_e32 v5, 0
	v_mov_b32_e32 v6, 0
	v_mov_b32_e32 v7, 0
	v_mov_b32_e32 v8, 0
	v_mov_b32_e32 v9, 0
	v_mov_b32_e32 v10, 0
	v_mov_b32_e32 v11, 0
	v_mov_b32_e32 v12, 0
	v_mov_b32_e32 v13, 0
	v_mov_b32_e32 v14, 0
	v_mov_b32_e32 v15, 0
	v_mov_b32_e32 v16, 0
	v_mov_b32_e32 v17, 0
	v_mov_b32_e32 v18, 0
	v_mov_b32_e32 v19, 0
	v_mov_b32_e32 v20, 0
	v_mov_b32_e32 v21, 0
	v_mov_b32_e32 v22, 0
	v_mov_b32_e32 v23, 0
	v_mov_b32_e32 v24, 0
	v_mov_b32_e32 v25, 0
	v_mov_b32_e32 v26, 0
	v_mov_b32_e32 v27, 0
	v_mov_b32_e32 v28, 0
	v_mov_b32_e32 v29, 0
	v_mov_b32_e32 v30, 0
	v_mov_b32_e32 v31, 0
	v_mov_b32_e32 v32, 0
	v_mov_b32_e32 v33, 0
	v_mov_b32_e32 v34, 0
	v_mov_b32_e32 v35, 0
	v_mov_b32_e32 v36, 0
	v_mov_b32_e32 v37, 0
	v_mov_b32_e32 v38, 0
	v_mov_b32_e32 v39, 0
	v_mov_b32_e32 v40, 0
	v_mov_b32_e32 v41, 0
	v_mov_b32_e32 v42, 0
	v_mov_b32_e32 v43, 0
	v_mov_b32_e32 v44, 0
	v_mov_b32_e32 v45, 0
	v_mov_b32_e32 v46, 0
	v_mov_b32_e32 v47, 0
	v_mov_b32_e32 v48, 0
	v_mov_b32_e32 v49, 0
	v_mov_b32_e32 v50, 0
	v_mov_b32_e32 v51, 0
	v_mov_b32_e32 v52, 0
	v_mov_b32_e32 v53, 0
	v_mov_b32_e32 v54, 0
	v_mov_b32_e32 v55, 0
	v_mov_b32_e32 v56, 0
	v_mov_b32_e32 v57, 0
	v_mov_b32_e32 v58, 0
	v_mov_b32_e32 v59, 0
	v_mov_b32_e32 v60, 0
	v_mov_b32_e32 v61, 0
	v_mov_b32_e32 v62, 0
	v_mov_b32_e32 v63, 0
	v_mov_b32_e32 v64, 0
	v_mov_b32_e32 v65, 0
	v_mov_b32_e32 v66, 0
	v_mov_b32_e32 v67, 0
	v_mov_b32_e32 v68, 0
	v_mov_b32_e32 v69, 0
	v_mov_b32_e32 v70, 0
	v_mov_b32_e32 v71, 0
	v_mov_b32_e32 v72, 0
	v_mov_b32_e32 v73, 0
	v_mov_b32_e32 v74, 0
	v_mov_b32_e32 v75, 0
	v_mov_b32_e32 v76, 0
	v_mov_b32_e32 v77, 0
	v_mov_b32_e32 v78, 0
	v_mov_b32_e32 v79, 0
	v_mov_b32_e32 v80, 0
	v_mov_b32_e32 v81, 0
	v_mov_b32_e32 v82, 0
	v_mov_b32_e32 v83, 0
	v_mov_b32_e32 v84, 0
	v_mov_b32_e32 v85, 0
	v_mov_b32_e32 v86, 0
	v_mov_b32_e32 v87, 0
	v_mov_b32_e32 v88, 0
	v_mov_b32_e32 v89, 0
	v_mov_b32_e32 v90, 0
	v_mov_b32_e32 v91, 0
	v_mov_b32_e32 v92, 0
	v_mov_b32_e32 v93, 0
	v_mov_b32_e32 v94, 0
	v_mov_b32_e32 v95, 0
	v_mov_b32_e32 v96, 0
	v_mov_b32_e32 v97, 0
	v_mov_b32_e32 v98, 0
	v_mov_b32_e32 v99, 0
	v_mov_b32_e32 v100, 0
	v_mov_b32_e32 v101, 0
	v_mov_b32_e32 v102, 0
	v_mov_b32_e32 v103, 0
	v_mov_b32_e32 v104, 0
	v_mov_b32_e32 v105, 0
	v_mov_b32_e32 v106, 0
	v_mov_b32_e32 v107, 0
	v_mov_b32_e32 v108, 0
	v_mov_b32_e32 v109, 0
	v_mov_b32_e32 v110, 0
	v_mov_b32_e32 v111, 0
	v_mov_b32_e32 v112, 0
	v_mov_b32_e32 v113, 0
	v_mov_b32_e32 v114, 0
	v_mov_b32_e32 v115, 0
	v_mov_b32_e32 v116, 0
	v_mov_b32_e32 v117, 0
	v_mov_b32_e32 v118, 0
	v_mov_b32_e32 v119, 0
	v_mov_b32_e32 v120, 0
	v_mov_b32_e32 v121, 0
	v_mov_b32_e32 v122, 0
	v_mov_b32_e32 v123, 0
	v_mov_b32_e32 v124, 0
	v_mov_b32_e32 v125, 0
	v_mov_b32_e32 v126, 0
	v_mov_b32_e32 v127, 0
	v_mov_b32_e32 v128, 0
	v_mov_b32_e32 v129, 0
	s_barrier
;     ...
;   __syncthreads();
;   G2_STAGE(0); G2_STAGE(1);
;   const int fsw = (0x78 >> (((r16 >> 2) & 3) * 2)) & 3;
;   const int aoff = (wm * 128 + r16) * 64 + ((quad ^ fsw) << 4);
;   const int boff = 16384 + (wn * 64 + r16) * 64 + ((quad ^ fsw) << 4);
;   for (int kt = 0; kt < nk; kt++) {
;     if (kt + 1 < nk) asm volatile("s_waitcnt vmcnt(6)" ::: "memory");
;     else asm volatile("s_waitcnt vmcnt(0)" ::: "memory");
;     __builtin_amdgcn_s_barrier();
;     asm volatile("" ::: "memory");
;     if (kt + 2 < nk) G2_STAGE(kt + 2);
;     const char* cS = smem + (kt % 3) * 24576;
;     bf16x8 xa[8], wb[4];
; #pragma unroll
;     for (int f = 0; f < 8; f++) xa[f] = *(const bf16x8*)(cS + aoff + f * 1024);
; #pragma unroll
;     for (int f = 0; f < 4; f++) wb[f] = *(const bf16x8*)(cS + boff + f * 1024);
; #pragma unroll
;     for (int nf = 0; nf < 4; nf++)
; #pragma unroll
;       for (int mf = 0; mf < 8; mf++)
;         acc[nf][mf] = __builtin_amdgcn_mfma_f32_16x16x32_bf16(wb[nf], xa[mf], acc[nf][mf], 0, 0, 0);
;   }
	s_add_i32 s40, s44, 0x0
	s_mov_b32 m0, s40
	v_lshl_add_u64 v[142:143], v[132:133], 0, s[2:3]
	global_load_lds_dwordx4 v[132:133], off
	s_addk_i32 m0, 0x1000
	s_nop 0
	global_load_lds_dwordx4 v[142:143], off
	v_lshl_add_u64 v[142:143], v[142:143], 0, s[2:3]
	s_addk_i32 m0, 0x1000
	s_nop 0
	global_load_lds_dwordx4 v[142:143], off
	v_lshl_add_u64 v[142:143], v[142:143], 0, s[2:3]
	s_addk_i32 m0, 0x1000
	s_nop 0
	global_load_lds_dwordx4 v[142:143], off
	s_addk_i32 m0, 0x1000
	v_lshl_add_u64 v[142:143], v[134:135], 0, s[2:3]
	s_nop 0
	global_load_lds_dwordx4 v[134:135], off
	s_addk_i32 m0, 0x1000
	v_lshl_add_u64 v[132:133], v[132:133], 0, s[36:37]
	s_nop 0
	global_load_lds_dwordx4 v[142:143], off
	v_lshl_add_u64 v[134:135], v[134:135], 0, s[8:9]
	s_nop 0
	s_add_i32 s40, s44, 0x6000
	s_mov_b32 m0, s40
	v_lshl_add_u64 v[142:143], v[132:133], 0, s[2:3]
	global_load_lds_dwordx4 v[132:133], off
	s_addk_i32 m0, 0x1000
	s_nop 0
	global_load_lds_dwordx4 v[142:143], off
	v_lshl_add_u64 v[142:143], v[142:143], 0, s[2:3]
	s_addk_i32 m0, 0x1000
	s_nop 0
	global_load_lds_dwordx4 v[142:143], off
	v_lshl_add_u64 v[142:143], v[142:143], 0, s[2:3]
	s_addk_i32 m0, 0x1000
	s_nop 0
	global_load_lds_dwordx4 v[142:143], off
	s_addk_i32 m0, 0x1000
	v_lshl_add_u64 v[142:143], v[134:135], 0, s[2:3]
	s_nop 0
	global_load_lds_dwordx4 v[134:135], off
	s_addk_i32 m0, 0x1000
	v_lshl_add_u64 v[132:133], v[132:133], 0, s[36:37]
	s_nop 0
	global_load_lds_dwordx4 v[142:143], off
	v_lshl_add_u64 v[134:135], v[134:135], 0, s[8:9]
	s_nop 0
	s_add_i32 s40, s44, 0xc000
	s_mov_b32 m0, s40
	v_lshl_add_u64 v[142:143], v[132:133], 0, s[2:3]
	global_load_lds_dwordx4 v[132:133], off
	s_addk_i32 m0, 0x1000
	s_nop 0
	global_load_lds_dwordx4 v[142:143], off
	v_lshl_add_u64 v[142:143], v[142:143], 0, s[2:3]
	s_addk_i32 m0, 0x1000
	s_nop 0
	global_load_lds_dwordx4 v[142:143], off
	v_lshl_add_u64 v[142:143], v[142:143], 0, s[2:3]
	s_addk_i32 m0, 0x1000
	s_nop 0
	global_load_lds_dwordx4 v[142:143], off
	s_addk_i32 m0, 0x1000
	v_lshl_add_u64 v[142:143], v[134:135], 0, s[2:3]
	s_nop 0
	global_load_lds_dwordx4 v[134:135], off
	s_addk_i32 m0, 0x1000
	v_lshl_add_u64 v[132:133], v[132:133], 0, s[36:37]
	s_nop 0
	global_load_lds_dwordx4 v[142:143], off
	v_lshl_add_u64 v[134:135], v[134:135], 0, s[8:9]
	s_nop 0
	s_waitcnt vmcnt(12)
	s_barrier
	ds_read_b128 v[146:149], v136 offset:0
	ds_read_b128 v[152:155], v136 offset:1024
	ds_read_b128 v[156:159], v136 offset:2048
	ds_read_b128 v[162:165], v136 offset:3072
	ds_read_b128 v[166:169], v136 offset:4096
	ds_read_b128 v[170:173], v136 offset:5120
	ds_read_b128 v[176:179], v136 offset:6144
	ds_read_b128 v[180:183], v136 offset:7168
	ds_read_b128 v[184:187], v137 offset:16384
	ds_read_b128 v[188:191], v137 offset:17408
	ds_read_b128 v[192:195], v137 offset:18432
	ds_read_b128 v[196:199], v137 offset:19456
	s_movk_i32 s38, 0x6000
	s_mov_b32 s39, 0
	s_movk_i32 s15, 14
.Lt0_loop:
	s_waitcnt vmcnt(6) lgkmcnt(0)
	s_barrier
	v_add_u32_e32 v144, s38, v136
	v_mfma_f32_16x16x32_bf16 v[126:129], v[184:187], v[146:149], v[126:129]
	ds_read_b128 v[200:203], v144 offset:0
	v_mfma_f32_16x16x32_bf16 v[122:125], v[184:187], v[152:155], v[122:125]
	ds_read_b128 v[204:207], v144 offset:1024
	v_mfma_f32_16x16x32_bf16 v[118:121], v[184:187], v[156:159], v[118:121]
	ds_read_b128 v[208:211], v144 offset:2048
	v_mfma_f32_16x16x32_bf16 v[114:117], v[184:187], v[162:165], v[114:117]
	ds_read_b128 v[212:215], v144 offset:3072
	v_mfma_f32_16x16x32_bf16 v[110:113], v[184:187], v[166:169], v[110:113]
	ds_read_b128 v[216:219], v144 offset:4096
	v_mfma_f32_16x16x32_bf16 v[106:109], v[184:187], v[170:173], v[106:109]
	ds_read_b128 v[220:223], v144 offset:5120
	v_mfma_f32_16x16x32_bf16 v[102:105], v[184:187], v[176:179], v[102:105]
	ds_read_b128 v[224:227], v144 offset:6144
	v_mfma_f32_16x16x32_bf16 v[98:101], v[184:187], v[180:183], v[98:101]
	ds_read_b128 v[228:231], v144 offset:7168
	v_mfma_f32_16x16x32_bf16 v[94:97], v[188:191], v[146:149], v[94:97]
	v_add_u32_e32 v144, s38, v137
	v_mfma_f32_16x16x32_bf16 v[90:93], v[188:191], v[152:155], v[90:93]
	v_mfma_f32_16x16x32_bf16 v[86:89], v[188:191], v[156:159], v[86:89]
	ds_read_b128 v[232:235], v144 offset:16384
	v_mfma_f32_16x16x32_bf16 v[82:85], v[188:191], v[162:165], v[82:85]
	ds_read_b128 v[236:239], v144 offset:17408
	v_mfma_f32_16x16x32_bf16 v[78:81], v[188:191], v[166:169], v[78:81]
	ds_read_b128 v[240:243], v144 offset:18432
	v_mfma_f32_16x16x32_bf16 v[74:77], v[188:191], v[170:173], v[74:77]
	ds_read_b128 v[244:247], v144 offset:19456
	s_add_i32 s40, s44, s39
	v_mfma_f32_16x16x32_bf16 v[70:73], v[188:191], v[176:179], v[70:73]
	s_mov_b32 m0, s40
	v_lshl_add_u64 v[142:143], v[132:133], 0, s[2:3]
	v_mfma_f32_16x16x32_bf16 v[66:69], v[188:191], v[180:183], v[66:69]
	global_load_lds_dwordx4 v[132:133], off
	s_addk_i32 m0, 0x1000
	v_mfma_f32_16x16x32_bf16 v[62:65], v[192:195], v[146:149], v[62:65]
	v_mfma_f32_16x16x32_bf16 v[58:61], v[192:195], v[152:155], v[58:61]
	v_mfma_f32_16x16x32_bf16 v[54:57], v[192:195], v[156:159], v[54:57]
	global_load_lds_dwordx4 v[142:143], off
	v_lshl_add_u64 v[142:143], v[142:143], 0, s[2:3]
	s_addk_i32 m0, 0x1000
	v_mfma_f32_16x16x32_bf16 v[50:53], v[192:195], v[162:165], v[50:53]
	v_mfma_f32_16x16x32_bf16 v[46:49], v[192:195], v[166:169], v[46:49]
	v_mfma_f32_16x16x32_bf16 v[42:45], v[192:195], v[170:173], v[42:45]
	global_load_lds_dwordx4 v[142:143], off
	v_lshl_add_u64 v[142:143], v[142:143], 0, s[2:3]
	s_addk_i32 m0, 0x1000
	v_mfma_f32_16x16x32_bf16 v[38:41], v[192:195], v[176:179], v[38:41]
	v_mfma_f32_16x16x32_bf16 v[34:37], v[192:195], v[180:183], v[34:37]
	v_mfma_f32_16x16x32_bf16 v[30:33], v[196:199], v[146:149], v[30:33]
	global_load_lds_dwordx4 v[142:143], off
	s_addk_i32 m0, 0x1000
	v_lshl_add_u64 v[142:143], v[134:135], 0, s[2:3]
	v_mfma_f32_16x16x32_bf16 v[26:29], v[196:199], v[152:155], v[26:29]
	v_mfma_f32_16x16x32_bf16 v[22:25], v[196:199], v[156:159], v[22:25]
	v_mfma_f32_16x16x32_bf16 v[18:21], v[196:199], v[162:165], v[18:21]
	global_load_lds_dwordx4 v[134:135], off
	s_addk_i32 m0, 0x1000
	v_lshl_add_u64 v[132:133], v[132:133], 0, s[36:37]
	v_mfma_f32_16x16x32_bf16 v[14:17], v[196:199], v[166:169], v[14:17]
	v_mfma_f32_16x16x32_bf16 v[10:13], v[196:199], v[170:173], v[10:13]
	v_mfma_f32_16x16x32_bf16 v[6:9], v[196:199], v[176:179], v[6:9]
	global_load_lds_dwordx4 v[142:143], off
	v_lshl_add_u64 v[134:135], v[134:135], 0, s[8:9]
	v_mfma_f32_16x16x32_bf16 v[2:5], v[196:199], v[180:183], v[2:5]
	s_mov_b32 s39, s38
	s_add_i32 s38, s38, 0x6000
	s_cmp_eq_u32 s38, 0x12000
	s_cselect_b32 s38, 0, s38
	s_waitcnt vmcnt(6) lgkmcnt(0)
	s_barrier
;     ...
;   for (int kt = 0; kt < nk; kt++) {
;     if (kt + 1 < nk) asm volatile("s_waitcnt vmcnt(6)" ::: "memory");
;     else asm volatile("s_waitcnt vmcnt(0)" ::: "memory");
;     __builtin_amdgcn_s_barrier();
;     asm volatile("" ::: "memory");
;     if (kt + 2 < nk) G2_STAGE(kt + 2);
;     const char* cS = smem + (kt % 3) * 24576;
;     bf16x8 xa[8], wb[4];
; #pragma unroll
;     for (int f = 0; f < 8; f++) xa[f] = *(const bf16x8*)(cS + aoff + f * 1024);
; #pragma unroll
;     for (int f = 0; f < 4; f++) wb[f] = *(const bf16x8*)(cS + boff + f * 1024);
; #pragma unroll
;     for (int nf = 0; nf < 4; nf++)
; #pragma unroll
;       for (int mf = 0; mf < 8; mf++)
;         acc[nf][mf] = __builtin_amdgcn_mfma_f32_16x16x32_bf16(wb[nf], xa[mf], acc[nf][mf], 0, 0, 0);
;   }
	v_add_u32_e32 v144, s38, v136
	v_mfma_f32_16x16x32_bf16 v[126:129], v[232:235], v[200:203], v[126:129]
	ds_read_b128 v[146:149], v144 offset:0
	v_mfma_f32_16x16x32_bf16 v[122:125], v[232:235], v[204:207], v[122:125]
	ds_read_b128 v[152:155], v144 offset:1024
	v_mfma_f32_16x16x32_bf16 v[118:121], v[232:235], v[208:211], v[118:121]
	ds_read_b128 v[156:159], v144 offset:2048
	v_mfma_f32_16x16x32_bf16 v[114:117], v[232:235], v[212:215], v[114:117]
	ds_read_b128 v[162:165], v144 offset:3072
	v_mfma_f32_16x16x32_bf16 v[110:113], v[232:235], v[216:219], v[110:113]
	ds_read_b128 v[166:169], v144 offset:4096
	v_mfma_f32_16x16x32_bf16 v[106:109], v[232:235], v[220:223], v[106:109]
	ds_read_b128 v[170:173], v144 offset:5120
	v_mfma_f32_16x16x32_bf16 v[102:105], v[232:235], v[224:227], v[102:105]
	ds_read_b128 v[176:179], v144 offset:6144
	v_mfma_f32_16x16x32_bf16 v[98:101], v[232:235], v[228:231], v[98:101]
	ds_read_b128 v[180:183], v144 offset:7168
	v_mfma_f32_16x16x32_bf16 v[94:97], v[236:239], v[200:203], v[94:97]
	v_add_u32_e32 v144, s38, v137
	v_mfma_f32_16x16x32_bf16 v[90:93], v[236:239], v[204:207], v[90:93]
	v_mfma_f32_16x16x32_bf16 v[86:89], v[236:239], v[208:211], v[86:89]
	ds_read_b128 v[184:187], v144 offset:16384
	v_mfma_f32_16x16x32_bf16 v[82:85], v[236:239], v[212:215], v[82:85]
	ds_read_b128 v[188:191], v144 offset:17408
	v_mfma_f32_16x16x32_bf16 v[78:81], v[236:239], v[216:219], v[78:81]
	ds_read_b128 v[192:195], v144 offset:18432
	v_mfma_f32_16x16x32_bf16 v[74:77], v[236:239], v[220:223], v[74:77]
	ds_read_b128 v[196:199], v144 offset:19456
	s_add_i32 s40, s44, s39
	v_mfma_f32_16x16x32_bf16 v[70:73], v[236:239], v[224:227], v[70:73]
	s_mov_b32 m0, s40
	v_lshl_add_u64 v[142:143], v[132:133], 0, s[2:3]
	v_mfma_f32_16x16x32_bf16 v[66:69], v[236:239], v[228:231], v[66:69]
	global_load_lds_dwordx4 v[132:133], off
	s_addk_i32 m0, 0x1000
	v_mfma_f32_16x16x32_bf16 v[62:65], v[240:243], v[200:203], v[62:65]
	v_mfma_f32_16x16x32_bf16 v[58:61], v[240:243], v[204:207], v[58:61]
	v_mfma_f32_16x16x32_bf16 v[54:57], v[240:243], v[208:211], v[54:57]
	global_load_lds_dwordx4 v[142:143], off
	v_lshl_add_u64 v[142:143], v[142:143], 0, s[2:3]
	s_addk_i32 m0, 0x1000
	v_mfma_f32_16x16x32_bf16 v[50:53], v[240:243], v[212:215], v[50:53]
	v_mfma_f32_16x16x32_bf16 v[46:49], v[240:243], v[216:219], v[46:49]
	v_mfma_f32_16x16x32_bf16 v[42:45], v[240:243], v[220:223], v[42:45]
	global_load_lds_dwordx4 v[142:143], off
	v_lshl_add_u64 v[142:143], v[142:143], 0, s[2:3]
	s_addk_i32 m0, 0x1000
	v_mfma_f32_16x16x32_bf16 v[38:41], v[240:243], v[224:227], v[38:41]
	v_mfma_f32_16x16x32_bf16 v[34:37], v[240:243], v[228:231], v[34:37]
	v_mfma_f32_16x16x32_bf16 v[30:33], v[244:247], v[200:203], v[30:33]
	global_load_lds_dwordx4 v[142:143], off
	s_addk_i32 m0, 0x1000
	v_lshl_add_u64 v[142:143], v[134:135], 0, s[2:3]
	v_mfma_f32_16x16x32_bf16 v[26:29], v[244:247], v[204:207], v[26:29]
	v_mfma_f32_16x16x32_bf16 v[22:25], v[244:247], v[208:211], v[22:25]
	v_mfma_f32_16x16x32_bf16 v[18:21], v[244:247], v[212:215], v[18:21]
	global_load_lds_dwordx4 v[134:135], off
	s_addk_i32 m0, 0x1000
	v_lshl_add_u64 v[132:133], v[132:133], 0, s[36:37]
	v_mfma_f32_16x16x32_bf16 v[14:17], v[244:247], v[216:219], v[14:17]
	v_mfma_f32_16x16x32_bf16 v[10:13], v[244:247], v[220:223], v[10:13]
	v_mfma_f32_16x16x32_bf16 v[6:9], v[244:247], v[224:227], v[6:9]
	global_load_lds_dwordx4 v[142:143], off
	v_lshl_add_u64 v[134:135], v[134:135], 0, s[8:9]
	v_mfma_f32_16x16x32_bf16 v[2:5], v[244:247], v[228:231], v[2:5]
	s_mov_b32 s39, s38
	s_add_i32 s38, s38, 0x6000
	s_cmp_eq_u32 s38, 0x12000
	s_cselect_b32 s38, 0, s38
	s_sub_i32 s15, s15, 1
	s_cmp_lg_u32 s15, 0
	s_cbranch_scc1 .Lt0_loop
	s_waitcnt vmcnt(6) lgkmcnt(0)
	s_barrier
	v_add_u32_e32 v144, s38, v136
	v_mfma_f32_16x16x32_bf16 v[126:129], v[184:187], v[146:149], v[126:129]
	ds_read_b128 v[200:203], v144 offset:0
	v_mfma_f32_16x16x32_bf16 v[122:125], v[184:187], v[152:155], v[122:125]
	ds_read_b128 v[204:207], v144 offset:1024
	v_mfma_f32_16x16x32_bf16 v[118:121], v[184:187], v[156:159], v[118:121]
	ds_read_b128 v[208:211], v144 offset:2048
	v_mfma_f32_16x16x32_bf16 v[114:117], v[184:187], v[162:165], v[114:117]
	ds_read_b128 v[212:215], v144 offset:3072
	v_mfma_f32_16x16x32_bf16 v[110:113], v[184:187], v[166:169], v[110:113]
	ds_read_b128 v[216:219], v144 offset:4096
	v_mfma_f32_16x16x32_bf16 v[106:109], v[184:187], v[170:173], v[106:109]
	ds_read_b128 v[220:223], v144 offset:5120
	v_mfma_f32_16x16x32_bf16 v[102:105], v[184:187], v[176:179], v[102:105]
	ds_read_b128 v[224:227], v144 offset:6144
	v_mfma_f32_16x16x32_bf16 v[98:101], v[184:187], v[180:183], v[98:101]
	ds_read_b128 v[228:231], v144 offset:7168
	v_mfma_f32_16x16x32_bf16 v[94:97], v[188:191], v[146:149], v[94:97]
	v_add_u32_e32 v144, s38, v137
	v_mfma_f32_16x16x32_bf16 v[90:93], v[188:191], v[152:155], v[90:93]
	v_mfma_f32_16x16x32_bf16 v[86:89], v[188:191], v[156:159], v[86:89]
	ds_read_b128 v[232:235], v144 offset:16384
	v_mfma_f32_16x16x32_bf16 v[82:85], v[188:191], v[162:165], v[82:85]
	ds_read_b128 v[236:239], v144 offset:17408
	v_mfma_f32_16x16x32_bf16 v[78:81], v[188:191], v[166:169], v[78:81]
	ds_read_b128 v[240:243], v144 offset:18432
	v_mfma_f32_16x16x32_bf16 v[74:77], v[188:191], v[170:173], v[74:77]
	ds_read_b128 v[244:247], v144 offset:19456
	s_add_i32 s40, s44, s39
	v_mfma_f32_16x16x32_bf16 v[70:73], v[188:191], v[176:179], v[70:73]
	s_mov_b32 m0, s40
	v_lshl_add_u64 v[142:143], v[132:133], 0, s[2:3]
	v_mfma_f32_16x16x32_bf16 v[66:69], v[188:191], v[180:183], v[66:69]
	global_load_lds_dwordx4 v[132:133], off
	s_addk_i32 m0, 0x1000
	v_mfma_f32_16x16x32_bf16 v[62:65], v[192:195], v[146:149], v[62:65]
;     ...
;   for (int kt = 0; kt < nk; kt++) {
;     if (kt + 1 < nk) asm volatile("s_waitcnt vmcnt(6)" ::: "memory");
;     else asm volatile("s_waitcnt vmcnt(0)" ::: "memory");
;     __builtin_amdgcn_s_barrier();
;     asm volatile("" ::: "memory");
;     if (kt + 2 < nk) G2_STAGE(kt + 2);
;     const char* cS = smem + (kt % 3) * 24576;
;     bf16x8 xa[8], wb[4];
; #pragma unroll
;     for (int f = 0; f < 8; f++) xa[f] = *(const bf16x8*)(cS + aoff + f * 1024);
; #pragma unroll
;     for (int f = 0; f < 4; f++) wb[f] = *(const bf16x8*)(cS + boff + f * 1024);
; #pragma unroll
;     for (int nf = 0; nf < 4; nf++)
; #pragma unroll
;       for (int mf = 0; mf < 8; mf++)
;         acc[nf][mf] = __builtin_amdgcn_mfma_f32_16x16x32_bf16(wb[nf], xa[mf], acc[nf][mf], 0, 0, 0);
;   }
	v_mfma_f32_16x16x32_bf16 v[58:61], v[192:195], v[152:155], v[58:61]
	v_mfma_f32_16x16x32_bf16 v[54:57], v[192:195], v[156:159], v[54:57]
	global_load_lds_dwordx4 v[142:143], off
	v_lshl_add_u64 v[142:143], v[142:143], 0, s[2:3]
	s_addk_i32 m0, 0x1000
	v_mfma_f32_16x16x32_bf16 v[50:53], v[192:195], v[162:165], v[50:53]
	v_mfma_f32_16x16x32_bf16 v[46:49], v[192:195], v[166:169], v[46:49]
	v_mfma_f32_16x16x32_bf16 v[42:45], v[192:195], v[170:173], v[42:45]
	global_load_lds_dwordx4 v[142:143], off
	v_lshl_add_u64 v[142:143], v[142:143], 0, s[2:3]
	s_addk_i32 m0, 0x1000
	v_mfma_f32_16x16x32_bf16 v[38:41], v[192:195], v[176:179], v[38:41]
	v_mfma_f32_16x16x32_bf16 v[34:37], v[192:195], v[180:183], v[34:37]
	v_mfma_f32_16x16x32_bf16 v[30:33], v[196:199], v[146:149], v[30:33]
	global_load_lds_dwordx4 v[142:143], off
	s_addk_i32 m0, 0x1000
	v_lshl_add_u64 v[142:143], v[134:135], 0, s[2:3]
	v_mfma_f32_16x16x32_bf16 v[26:29], v[196:199], v[152:155], v[26:29]
	v_mfma_f32_16x16x32_bf16 v[22:25], v[196:199], v[156:159], v[22:25]
	v_mfma_f32_16x16x32_bf16 v[18:21], v[196:199], v[162:165], v[18:21]
	global_load_lds_dwordx4 v[134:135], off
	s_addk_i32 m0, 0x1000
	v_lshl_add_u64 v[132:133], v[132:133], 0, s[36:37]
	v_mfma_f32_16x16x32_bf16 v[14:17], v[196:199], v[166:169], v[14:17]
	v_mfma_f32_16x16x32_bf16 v[10:13], v[196:199], v[170:173], v[10:13]
	v_mfma_f32_16x16x32_bf16 v[6:9], v[196:199], v[176:179], v[6:9]
	global_load_lds_dwordx4 v[142:143], off
	v_lshl_add_u64 v[134:135], v[134:135], 0, s[8:9]
	v_mfma_f32_16x16x32_bf16 v[2:5], v[196:199], v[180:183], v[2:5]
	s_mov_b32 s39, s38
	s_add_i32 s38, s38, 0x6000
	s_cmp_eq_u32 s38, 0x12000
	s_cselect_b32 s38, 0, s38
	s_waitcnt vmcnt(6) lgkmcnt(0)
	s_barrier
	v_add_u32_e32 v144, s38, v136
	v_mfma_f32_16x16x32_bf16 v[126:129], v[232:235], v[200:203], v[126:129]
	ds_read_b128 v[146:149], v144 offset:0
	v_mfma_f32_16x16x32_bf16 v[122:125], v[232:235], v[204:207], v[122:125]
	ds_read_b128 v[152:155], v144 offset:1024
	v_mfma_f32_16x16x32_bf16 v[118:121], v[232:235], v[208:211], v[118:121]
	ds_read_b128 v[156:159], v144 offset:2048
	v_mfma_f32_16x16x32_bf16 v[114:117], v[232:235], v[212:215], v[114:117]
	ds_read_b128 v[162:165], v144 offset:3072
	v_mfma_f32_16x16x32_bf16 v[110:113], v[232:235], v[216:219], v[110:113]
	ds_read_b128 v[166:169], v144 offset:4096
	v_mfma_f32_16x16x32_bf16 v[106:109], v[232:235], v[220:223], v[106:109]
	ds_read_b128 v[170:173], v144 offset:5120
	v_mfma_f32_16x16x32_bf16 v[102:105], v[232:235], v[224:227], v[102:105]
	ds_read_b128 v[176:179], v144 offset:6144
	v_mfma_f32_16x16x32_bf16 v[98:101], v[232:235], v[228:231], v[98:101]
	ds_read_b128 v[180:183], v144 offset:7168
	v_mfma_f32_16x16x32_bf16 v[94:97], v[236:239], v[200:203], v[94:97]
	v_add_u32_e32 v144, s38, v137
	v_mfma_f32_16x16x32_bf16 v[90:93], v[236:239], v[204:207], v[90:93]
	v_mfma_f32_16x16x32_bf16 v[86:89], v[236:239], v[208:211], v[86:89]
	ds_read_b128 v[184:187], v144 offset:16384
	v_mfma_f32_16x16x32_bf16 v[82:85], v[236:239], v[212:215], v[82:85]
	ds_read_b128 v[188:191], v144 offset:17408
	v_mfma_f32_16x16x32_bf16 v[78:81], v[236:239], v[216:219], v[78:81]
	ds_read_b128 v[192:195], v144 offset:18432
	v_mfma_f32_16x16x32_bf16 v[74:77], v[236:239], v[220:223], v[74:77]
	ds_read_b128 v[196:199], v144 offset:19456
	v_mfma_f32_16x16x32_bf16 v[70:73], v[236:239], v[224:227], v[70:73]
	v_mfma_f32_16x16x32_bf16 v[66:69], v[236:239], v[228:231], v[66:69]
	v_mfma_f32_16x16x32_bf16 v[62:65], v[240:243], v[200:203], v[62:65]
	v_mfma_f32_16x16x32_bf16 v[58:61], v[240:243], v[204:207], v[58:61]
	v_mfma_f32_16x16x32_bf16 v[54:57], v[240:243], v[208:211], v[54:57]
	v_mfma_f32_16x16x32_bf16 v[50:53], v[240:243], v[212:215], v[50:53]
	v_mfma_f32_16x16x32_bf16 v[46:49], v[240:243], v[216:219], v[46:49]
	v_mfma_f32_16x16x32_bf16 v[42:45], v[240:243], v[220:223], v[42:45]
	v_mfma_f32_16x16x32_bf16 v[38:41], v[240:243], v[224:227], v[38:41]
	v_mfma_f32_16x16x32_bf16 v[34:37], v[240:243], v[228:231], v[34:37]
	v_mfma_f32_16x16x32_bf16 v[30:33], v[244:247], v[200:203], v[30:33]
	v_mfma_f32_16x16x32_bf16 v[26:29], v[244:247], v[204:207], v[26:29]
	v_mfma_f32_16x16x32_bf16 v[22:25], v[244:247], v[208:211], v[22:25]
	v_mfma_f32_16x16x32_bf16 v[18:21], v[244:247], v[212:215], v[18:21]
	v_mfma_f32_16x16x32_bf16 v[14:17], v[244:247], v[216:219], v[14:17]
	v_mfma_f32_16x16x32_bf16 v[10:13], v[244:247], v[220:223], v[10:13]
	v_mfma_f32_16x16x32_bf16 v[6:9], v[244:247], v[224:227], v[6:9]
	v_mfma_f32_16x16x32_bf16 v[2:5], v[244:247], v[228:231], v[2:5]
	s_mov_b32 s39, s38
	s_add_i32 s38, s38, 0x6000
	s_cmp_eq_u32 s38, 0x12000
	s_cselect_b32 s38, 0, s38
	s_waitcnt vmcnt(0) lgkmcnt(0)
	s_barrier
;     ...
;   for (int kt = 0; kt < nk; kt++) {
;     if (kt + 1 < nk) asm volatile("s_waitcnt vmcnt(6)" ::: "memory");
;     else asm volatile("s_waitcnt vmcnt(0)" ::: "memory");
;     __builtin_amdgcn_s_barrier();
;     asm volatile("" ::: "memory");
;     if (kt + 2 < nk) G2_STAGE(kt + 2);
;     const char* cS = smem + (kt % 3) * 24576;
;     bf16x8 xa[8], wb[4];
; #pragma unroll
;     for (int f = 0; f < 8; f++) xa[f] = *(const bf16x8*)(cS + aoff + f * 1024);
; #pragma unroll
;     for (int f = 0; f < 4; f++) wb[f] = *(const bf16x8*)(cS + boff + f * 1024);
; #pragma unroll
;     for (int nf = 0; nf < 4; nf++)
; #pragma unroll
;       for (int mf = 0; mf < 8; mf++)
;         acc[nf][mf] = __builtin_amdgcn_mfma_f32_16x16x32_bf16(wb[nf], xa[mf], acc[nf][mf], 0, 0, 0);
;   }
	v_add_u32_e32 v144, s38, v136
	v_mfma_f32_16x16x32_bf16 v[126:129], v[184:187], v[146:149], v[126:129]
	ds_read_b128 v[200:203], v144 offset:0
	v_mfma_f32_16x16x32_bf16 v[122:125], v[184:187], v[152:155], v[122:125]
	ds_read_b128 v[204:207], v144 offset:1024
	v_mfma_f32_16x16x32_bf16 v[118:121], v[184:187], v[156:159], v[118:121]
	ds_read_b128 v[208:211], v144 offset:2048
	v_mfma_f32_16x16x32_bf16 v[114:117], v[184:187], v[162:165], v[114:117]
	ds_read_b128 v[212:215], v144 offset:3072
	v_mfma_f32_16x16x32_bf16 v[110:113], v[184:187], v[166:169], v[110:113]
	ds_read_b128 v[216:219], v144 offset:4096
	v_mfma_f32_16x16x32_bf16 v[106:109], v[184:187], v[170:173], v[106:109]
	ds_read_b128 v[220:223], v144 offset:5120
	v_mfma_f32_16x16x32_bf16 v[102:105], v[184:187], v[176:179], v[102:105]
	ds_read_b128 v[224:227], v144 offset:6144
	v_mfma_f32_16x16x32_bf16 v[98:101], v[184:187], v[180:183], v[98:101]
	ds_read_b128 v[228:231], v144 offset:7168
	v_mfma_f32_16x16x32_bf16 v[94:97], v[188:191], v[146:149], v[94:97]
	v_add_u32_e32 v144, s38, v137
	v_mfma_f32_16x16x32_bf16 v[90:93], v[188:191], v[152:155], v[90:93]
	v_mfma_f32_16x16x32_bf16 v[86:89], v[188:191], v[156:159], v[86:89]
	ds_read_b128 v[232:235], v144 offset:16384
	v_mfma_f32_16x16x32_bf16 v[82:85], v[188:191], v[162:165], v[82:85]
	ds_read_b128 v[236:239], v144 offset:17408
	v_mfma_f32_16x16x32_bf16 v[78:81], v[188:191], v[166:169], v[78:81]
	ds_read_b128 v[240:243], v144 offset:18432
	v_mfma_f32_16x16x32_bf16 v[74:77], v[188:191], v[170:173], v[74:77]
	ds_read_b128 v[244:247], v144 offset:19456
	v_mfma_f32_16x16x32_bf16 v[70:73], v[188:191], v[176:179], v[70:73]
	v_mfma_f32_16x16x32_bf16 v[66:69], v[188:191], v[180:183], v[66:69]
	v_mfma_f32_16x16x32_bf16 v[62:65], v[192:195], v[146:149], v[62:65]
	v_mfma_f32_16x16x32_bf16 v[58:61], v[192:195], v[152:155], v[58:61]
	v_mfma_f32_16x16x32_bf16 v[54:57], v[192:195], v[156:159], v[54:57]
	v_mfma_f32_16x16x32_bf16 v[50:53], v[192:195], v[162:165], v[50:53]
	v_mfma_f32_16x16x32_bf16 v[46:49], v[192:195], v[166:169], v[46:49]
	v_mfma_f32_16x16x32_bf16 v[42:45], v[192:195], v[170:173], v[42:45]
	v_mfma_f32_16x16x32_bf16 v[38:41], v[192:195], v[176:179], v[38:41]
	v_mfma_f32_16x16x32_bf16 v[34:37], v[192:195], v[180:183], v[34:37]
	v_mfma_f32_16x16x32_bf16 v[30:33], v[196:199], v[146:149], v[30:33]
	v_mfma_f32_16x16x32_bf16 v[26:29], v[196:199], v[152:155], v[26:29]
	v_mfma_f32_16x16x32_bf16 v[22:25], v[196:199], v[156:159], v[22:25]
	v_mfma_f32_16x16x32_bf16 v[18:21], v[196:199], v[162:165], v[18:21]
	v_mfma_f32_16x16x32_bf16 v[14:17], v[196:199], v[166:169], v[14:17]
	v_mfma_f32_16x16x32_bf16 v[10:13], v[196:199], v[170:173], v[10:13]
	v_mfma_f32_16x16x32_bf16 v[6:9], v[196:199], v[176:179], v[6:9]
	v_mfma_f32_16x16x32_bf16 v[2:5], v[196:199], v[180:183], v[2:5]
	s_mov_b32 s39, s38
	s_add_i32 s38, s38, 0x6000
	s_cmp_eq_u32 s38, 0x12000
	s_cselect_b32 s38, 0, s38
	s_waitcnt lgkmcnt(0)
; DEVI unsigned pack2(float a, float b) { return __builtin_bit_cast(unsigned, __builtin_convertvector((f32x2_t){a, b}, bf16x2_t)); }
;     ...
;     for (int nf = 0; nf < 4; nf++)
; #pragma unroll
;       for (int mf = 0; mf < 8; mf++)
;         acc[nf][mf] = __builtin_amdgcn_mfma_f32_16x16x32_bf16(wb[nf], xa[mf], acc[nf][mf], 0, 0, 0);
;     ...
;         } else {
;           u32x2 pk; pk[0] = pack2(a[0], a[1]); pk[1] = pack2(a[2], a[3]);
;           *(u32x2*)(outb + (size_t)row * ldc + col) = pk;
;         }
	v_mfma_f32_16x16x32_bf16 v[126:129], v[232:235], v[200:203], v[126:129]
	v_mfma_f32_16x16x32_bf16 v[122:125], v[232:235], v[204:207], v[122:125]
	v_mfma_f32_16x16x32_bf16 v[118:121], v[232:235], v[208:211], v[118:121]
	v_mfma_f32_16x16x32_bf16 v[114:117], v[232:235], v[212:215], v[114:117]
	v_mfma_f32_16x16x32_bf16 v[110:113], v[232:235], v[216:219], v[110:113]
	v_mfma_f32_16x16x32_bf16 v[106:109], v[232:235], v[220:223], v[106:109]
	v_mfma_f32_16x16x32_bf16 v[102:105], v[232:235], v[224:227], v[102:105]
	v_mfma_f32_16x16x32_bf16 v[98:101], v[232:235], v[228:231], v[98:101]
	v_mfma_f32_16x16x32_bf16 v[94:97], v[236:239], v[200:203], v[94:97]
	v_mfma_f32_16x16x32_bf16 v[90:93], v[236:239], v[204:207], v[90:93]
	v_mfma_f32_16x16x32_bf16 v[86:89], v[236:239], v[208:211], v[86:89]
	v_mfma_f32_16x16x32_bf16 v[82:85], v[236:239], v[212:215], v[82:85]
	v_mfma_f32_16x16x32_bf16 v[78:81], v[236:239], v[216:219], v[78:81]
	v_mfma_f32_16x16x32_bf16 v[74:77], v[236:239], v[220:223], v[74:77]
	v_mfma_f32_16x16x32_bf16 v[70:73], v[236:239], v[224:227], v[70:73]
	v_mfma_f32_16x16x32_bf16 v[66:69], v[236:239], v[228:231], v[66:69]
	v_mfma_f32_16x16x32_bf16 v[62:65], v[240:243], v[200:203], v[62:65]
	v_mfma_f32_16x16x32_bf16 v[58:61], v[240:243], v[204:207], v[58:61]
	v_mfma_f32_16x16x32_bf16 v[54:57], v[240:243], v[208:211], v[54:57]
	v_mfma_f32_16x16x32_bf16 v[50:53], v[240:243], v[212:215], v[50:53]
	v_mfma_f32_16x16x32_bf16 v[46:49], v[240:243], v[216:219], v[46:49]
	v_mfma_f32_16x16x32_bf16 v[42:45], v[240:243], v[220:223], v[42:45]
	v_mfma_f32_16x16x32_bf16 v[38:41], v[240:243], v[224:227], v[38:41]
	v_mfma_f32_16x16x32_bf16 v[34:37], v[240:243], v[228:231], v[34:37]
	v_mfma_f32_16x16x32_bf16 v[30:33], v[244:247], v[200:203], v[30:33]
	v_mfma_f32_16x16x32_bf16 v[26:29], v[244:247], v[204:207], v[26:29]
	v_mfma_f32_16x16x32_bf16 v[22:25], v[244:247], v[208:211], v[22:25]
	v_mfma_f32_16x16x32_bf16 v[18:21], v[244:247], v[212:215], v[18:21]
	v_mfma_f32_16x16x32_bf16 v[14:17], v[244:247], v[216:219], v[14:17]
	v_mfma_f32_16x16x32_bf16 v[10:13], v[244:247], v[220:223], v[10:13]
	v_mfma_f32_16x16x32_bf16 v[6:9], v[244:247], v[224:227], v[6:9]
	v_mfma_f32_16x16x32_bf16 v[2:5], v[244:247], v[228:231], v[2:5]
	s_mov_b32 m0, s41
	s_mov_b32 s8, 0x14000
	s_mov_b32 s9, 0
	s_nop 7
	v_cvt_pk_bf16_f32 v126, v126, v127
	v_cvt_pk_bf16_f32 v127, v128, v129
	v_cvt_pk_bf16_f32 v128, v94, v95
	v_cvt_pk_bf16_f32 v129, v96, v97
	v_cvt_pk_bf16_f32 v62, v62, v63
	v_cvt_pk_bf16_f32 v63, v64, v65
	v_cvt_pk_bf16_f32 v64, v30, v31
	v_cvt_pk_bf16_f32 v65, v32, v33
	v_permlane16_swap_b32_e32 v126, v128
	v_permlane16_swap_b32_e32 v127, v129
	v_permlane16_swap_b32_e32 v62, v64
	v_permlane16_swap_b32_e32 v63, v65
	global_store_dwordx4 v[140:141], v[126:129], off offset:0
	global_store_dwordx4 v[140:141], v[62:65], off offset:64
	v_lshl_add_u64 v[140:141], v[140:141], 0, s[8:9]
	v_cvt_pk_bf16_f32 v122, v122, v123
	v_cvt_pk_bf16_f32 v123, v124, v125
	v_cvt_pk_bf16_f32 v124, v90, v91
	v_cvt_pk_bf16_f32 v125, v92, v93
	v_cvt_pk_bf16_f32 v58, v58, v59
	v_cvt_pk_bf16_f32 v59, v60, v61
	v_cvt_pk_bf16_f32 v60, v26, v27
	v_cvt_pk_bf16_f32 v61, v28, v29
	v_permlane16_swap_b32_e32 v122, v124
	v_permlane16_swap_b32_e32 v123, v125
	v_permlane16_swap_b32_e32 v58, v60
	v_permlane16_swap_b32_e32 v59, v61
	global_store_dwordx4 v[140:141], v[122:125], off offset:0
	global_store_dwordx4 v[140:141], v[58:61], off offset:64
	v_lshl_add_u64 v[140:141], v[140:141], 0, s[8:9]
	v_cvt_pk_bf16_f32 v118, v118, v119
	v_cvt_pk_bf16_f32 v119, v120, v121
	v_cvt_pk_bf16_f32 v120, v86, v87
	v_cvt_pk_bf16_f32 v121, v88, v89
	v_cvt_pk_bf16_f32 v54, v54, v55
	v_cvt_pk_bf16_f32 v55, v56, v57
	v_cvt_pk_bf16_f32 v56, v22, v23
	v_cvt_pk_bf16_f32 v57, v24, v25
	v_permlane16_swap_b32_e32 v118, v120
	v_permlane16_swap_b32_e32 v119, v121
	v_permlane16_swap_b32_e32 v54, v56
	v_permlane16_swap_b32_e32 v55, v57
	global_store_dwordx4 v[140:141], v[118:121], off offset:0
	global_store_dwordx4 v[140:141], v[54:57], off offset:64
	v_lshl_add_u64 v[140:141], v[140:141], 0, s[8:9]
	v_cvt_pk_bf16_f32 v114, v114, v115
	v_cvt_pk_bf16_f32 v115, v116, v117
	v_cvt_pk_bf16_f32 v116, v82, v83
	v_cvt_pk_bf16_f32 v117, v84, v85
	v_cvt_pk_bf16_f32 v50, v50, v51
	v_cvt_pk_bf16_f32 v51, v52, v53
	v_cvt_pk_bf16_f32 v52, v18, v19
	v_cvt_pk_bf16_f32 v53, v20, v21
	v_permlane16_swap_b32_e32 v114, v116
	v_permlane16_swap_b32_e32 v115, v117
	v_permlane16_swap_b32_e32 v50, v52
	v_permlane16_swap_b32_e32 v51, v53
	global_store_dwordx4 v[140:141], v[114:117], off offset:0
	global_store_dwordx4 v[140:141], v[50:53], off offset:64
	v_lshl_add_u64 v[140:141], v[140:141], 0, s[8:9]
	v_cvt_pk_bf16_f32 v110, v110, v111
	v_cvt_pk_bf16_f32 v111, v112, v113
	v_cvt_pk_bf16_f32 v112, v78, v79
	v_cvt_pk_bf16_f32 v113, v80, v81
	v_cvt_pk_bf16_f32 v46, v46, v47
	v_cvt_pk_bf16_f32 v47, v48, v49
	v_cvt_pk_bf16_f32 v48, v14, v15
	v_cvt_pk_bf16_f32 v49, v16, v17
	v_permlane16_swap_b32_e32 v110, v112
	v_permlane16_swap_b32_e32 v111, v113
	v_permlane16_swap_b32_e32 v46, v48
	v_permlane16_swap_b32_e32 v47, v49
	global_store_dwordx4 v[140:141], v[110:113], off offset:0
	global_store_dwordx4 v[140:141], v[46:49], off offset:64
	v_lshl_add_u64 v[140:141], v[140:141], 0, s[8:9]
	v_cvt_pk_bf16_f32 v106, v106, v107
	v_cvt_pk_bf16_f32 v107, v108, v109
	v_cvt_pk_bf16_f32 v108, v74, v75
	v_cvt_pk_bf16_f32 v109, v76, v77
	v_cvt_pk_bf16_f32 v42, v42, v43
	v_cvt_pk_bf16_f32 v43, v44, v45
	v_cvt_pk_bf16_f32 v44, v10, v11
	v_cvt_pk_bf16_f32 v45, v12, v13
	v_permlane16_swap_b32_e32 v106, v108
	v_permlane16_swap_b32_e32 v107, v109
	v_permlane16_swap_b32_e32 v42, v44
	v_permlane16_swap_b32_e32 v43, v45
	global_store_dwordx4 v[140:141], v[106:109], off offset:0
	global_store_dwordx4 v[140:141], v[42:45], off offset:64
	v_lshl_add_u64 v[140:141], v[140:141], 0, s[8:9]
	v_cvt_pk_bf16_f32 v102, v102, v103
	v_cvt_pk_bf16_f32 v103, v104, v105
	v_cvt_pk_bf16_f32 v104, v70, v71
	v_cvt_pk_bf16_f32 v105, v72, v73
	v_cvt_pk_bf16_f32 v38, v38, v39
	v_cvt_pk_bf16_f32 v39, v40, v41
	v_cvt_pk_bf16_f32 v40, v6, v7
	v_cvt_pk_bf16_f32 v41, v8, v9
	v_permlane16_swap_b32_e32 v102, v104
	v_permlane16_swap_b32_e32 v103, v105
	v_permlane16_swap_b32_e32 v38, v40
	v_permlane16_swap_b32_e32 v39, v41
	global_store_dwordx4 v[140:141], v[102:105], off offset:0
	global_store_dwordx4 v[140:141], v[38:41], off offset:64
	v_lshl_add_u64 v[140:141], v[140:141], 0, s[8:9]
	v_cvt_pk_bf16_f32 v98, v98, v99
	v_cvt_pk_bf16_f32 v99, v100, v101
	v_cvt_pk_bf16_f32 v100, v66, v67
	v_cvt_pk_bf16_f32 v101, v68, v69
	v_cvt_pk_bf16_f32 v34, v34, v35
	v_cvt_pk_bf16_f32 v35, v36, v37
	v_cvt_pk_bf16_f32 v36, v2, v3
	v_cvt_pk_bf16_f32 v37, v4, v5
	v_permlane16_swap_b32_e32 v98, v100
	v_permlane16_swap_b32_e32 v99, v101
	v_permlane16_swap_b32_e32 v34, v36
	v_permlane16_swap_b32_e32 v35, v37
	global_store_dwordx4 v[140:141], v[98:101], off offset:0
	global_store_dwordx4 v[140:141], v[34:37], off offset:64
	s_branch .LBB0_886
